# stack13 with the K-loop priority flips removed and one static s_setprio 1 for waves 4-7 at kernel entry
# speedup vs baseline: 1.0016x; 1.0001x over previous
; #define LAS __attribute__((address_space(3)))
; __global__ void __launch_bounds__(512, 2) fwd_mega(Args args) {
;     extern __shared__ __attribute__((aligned(16))) unsigned char lds_raw[];
;     LAS unsigned char* lds = (LAS unsigned char*)lds_raw;
;     cg::grid_group grid = cg::this_grid();
;     const int G = gridDim.x, bx = blockIdx.x;
;     LAS unsigned long long* ptab = (LAS unsigned long long*)(lds + 147200);
;     { const int tid = threadIdx.x;
;     if (tid < 26) ptab[tid] = (unsigned long long)args.in[tid];
;     if (tid == 26) ptab[26] = (unsigned long long)args.out;
;     if (tid == 27) ptab[27] = (unsigned long long)args.ws;
;     if (tid == 28) { ((volatile LAS unsigned*)(lds + 147200 + 240))[0] = 0u; ((volatile LAS unsigned*)(lds + 147200 + 240))[1] = 0u; } }
;     __syncthreads();
_Z8fwd_mega4Args:
	s_load_dwordx2 s[52:53], s[0:1], 0xe8
	s_load_dword s10, s[0:1], 0xf0
	s_add_u32 s4, s0, 0xe8
	s_addc_u32 s5, s1, 0
	v_and_b32_e32 v176, 0x3ff, v0
	v_writelane_b32 v253, s4, 0
	v_cmp_gt_u32_e32 vcc, 26, v176
	s_nop 0
	v_writelane_b32 v253, s5, 1
	v_readfirstlane_b32 s98, v176
	s_lshr_b32 s98, s98, 6
	s_cmp_ge_u32 s98, 4
	s_cbranch_scc0 .Lprio_done
	s_setprio 1
.Lprio_done:
	s_and_saveexec_b64 s[4:5], vcc
	s_cbranch_execz .LBB0_2
	v_lshlrev_b32_e32 v1, 3, v176
	global_load_dwordx2 v[2:3], v1, s[0:1]
	v_add_u32_e32 v1, 0, v1
	v_add_u32_e32 v1, 0x23f00, v1
	s_waitcnt vmcnt(0)
	ds_write_b64 v1, v[2:3]

; #define PG8_STAGE(bufoff, gbase, voff) do { _Pragma("unroll") for (int _i = 0; _i < 2; ++_i) \
;         __builtin_amdgcn_global_load_lds((const unsigned*)((const char*)(gbase) + (voff)[_i]), (PG8_LAS unsigned*)(lds + (bufoff) + ldsw + _i * 8192), 16, 0, 0); } while (0)
; #define PG8_LDA(dst, b, h) do { _Pragma("unroll") for (int m = 0; m < 4; ++m) _Pragma("unroll") for (int k = 0; k < 2; ++k) dst[m][k] = *(const PG8_LAS bf16x8*)(lds + PG8_SA(b, h) + aoff + m * 2048 + k * 1024); } while (0)
; #define PG8_LDB(dst, b, h) do { _Pragma("unroll") for (int n = 0; n < 2; ++n) _Pragma("unroll") for (int k = 0; k < 2; ++k) dst[n][k] = *(const PG8_LAS bf16x8*)(lds + PG8_SB(b, h) + boff + n * 2048 + k * 1024); } while (0)
; #define PG8_MMA(ai, bj, At, Bt) do { __builtin_amdgcn_s_setprio(1); _Pragma("unroll") for (int m = 0; m < 4; ++m) _Pragma("unroll") for (int n = 0; n < 2; ++n) _Pragma("unroll") for (int k = 0; k < 2; ++k) \
;         acc[ai][bj][m][n] = __builtin_amdgcn_mfma_f32_16x16x32_bf16(Bt[n][k], At[m][k], acc[ai][bj][m][n], 0, 0, 0); __builtin_amdgcn_s_setprio(0); } while (0)
; #define PG8_WAIT_V(n) asm volatile("s_waitcnt vmcnt(" #n ")" ::: "memory")
; #define PG8_WAIT_L(n) asm volatile("s_waitcnt lgkmcnt(" #n ")" ::: "memory")
; #define PG8_BAR __builtin_amdgcn_s_barrier()
; #define PG8_SCHED __builtin_amdgcn_sched_barrier(0)
; template <class Epi, class Sched, bool ALIGN_EPI = false, bool SP2 = false>
; __device__ __forceinline__ void gemm_phase(PG8_LAS unsigned char* lds, const Gemm g, const Sched& S, const Epi& E) {
;     ...
;             PG8_LDB(B0, 0, 0); PG8_LDB(B1, 0, 1); PG8_SCHED; PG8_LDA(At, 0, 0); PG8_STAGE(PG8_SA(1, 1), a1 + hstep, voffA);
;             PG8_WAIT_V(8); PG8_WAIT_L(0); PG8_BAR; PG8_MMA(0, 0, At, B0); PG8_MMA(0, 1, At, B1); PG8_BAR; PG8_SCHED;
;             PG8_LDA(At, 0, 1); PG8_STAGE(PG8_SB(0, 0), b2, voffB); PG8_STAGE(PG8_SB(0, 1), b2 + hstep, voffB); PG8_STAGE(PG8_SA(0, 0), a2, voffA);
.LBB0_165:
	s_add_u32 s68, s42, 0xfff80080
	s_addc_u32 s69, s43, -1
	s_add_i32 s82, 0, 0x10000
	s_cmp_eq_u32 s71, 28
	s_cselect_b32 s81, s47, s69
	s_cselect_b32 s80, s55, s68
	v_add_u32_e32 v144, s82, v147
	s_cselect_b32 s79, s45, s63
	s_cselect_b32 s78, s58, s59
	s_add_i32 s83, 0, 0x14000
	ds_read_b128 v[140:143], v144
	ds_read_b128 v[156:159], v144 offset:1024
	ds_read_b128 v[160:163], v144 offset:2048
	ds_read_b128 v[164:167], v144 offset:3072
	v_add_u32_e32 v144, s83, v147
	ds_read_b128 v[168:171], v144
	ds_read_b128 v[172:175], v144 offset:1024
	ds_read_b128 v[192:195], v144 offset:2048
	ds_read_b128 v[196:199], v144 offset:3072
	v_lshl_add_u64 v[150:151], s[42:43], 0, v[136:137]
	s_add_i32 m0, s14, 0xc000
	ds_read_b128 v[200:203], v149
	ds_read_b128 v[204:207], v149 offset:1024
	ds_read_b128 v[208:211], v149 offset:2048
	ds_read_b128 v[212:215], v149 offset:3072
	ds_read_b128 v[216:219], v149 offset:4096
	ds_read_b128 v[220:223], v149 offset:5120
	ds_read_b128 v[224:227], v149 offset:6144
	ds_read_b128 v[228:231], v149 offset:7168
	global_load_lds_dwordx4 v[150:151], off
	v_lshl_add_u64 v[150:151], s[42:43], 0, v[138:139]
	s_add_i32 m0, s14, 0xe000
	s_nop 0
	global_load_lds_dwordx4 v[150:151], off
	s_waitcnt vmcnt(8)
	s_waitcnt lgkmcnt(0)
	s_barrier
	v_mfma_f32_16x16x32_bf16 v[124:127], v[140:143], v[200:203], v[124:127]
	v_mfma_f32_16x16x32_bf16 v[120:123], v[160:163], v[200:203], v[120:123]
	v_mfma_f32_16x16x32_bf16 v[108:111], v[140:143], v[208:211], v[108:111]
	v_mfma_f32_16x16x32_bf16 v[104:107], v[160:163], v[208:211], v[104:107]
	v_mfma_f32_16x16x32_bf16 v[92:95], v[140:143], v[216:219], v[92:95]
	v_mfma_f32_16x16x32_bf16 v[88:91], v[160:163], v[216:219], v[88:91]
	v_mfma_f32_16x16x32_bf16 v[76:79], v[140:143], v[224:227], v[76:79]
	v_mfma_f32_16x16x32_bf16 v[72:75], v[160:163], v[224:227], v[72:75]
	v_mfma_f32_16x16x32_bf16 v[124:127], v[156:159], v[204:207], v[124:127]
	v_mfma_f32_16x16x32_bf16 v[120:123], v[164:167], v[204:207], v[120:123]
	v_mfma_f32_16x16x32_bf16 v[108:111], v[156:159], v[212:215], v[108:111]
	v_mfma_f32_16x16x32_bf16 v[104:107], v[164:167], v[212:215], v[104:107]
	v_mfma_f32_16x16x32_bf16 v[92:95], v[156:159], v[220:223], v[92:95]
	v_mfma_f32_16x16x32_bf16 v[88:91], v[164:167], v[220:223], v[88:91]
	v_mfma_f32_16x16x32_bf16 v[76:79], v[156:159], v[228:231], v[76:79]
	v_mfma_f32_16x16x32_bf16 v[72:75], v[164:167], v[228:231], v[72:75]
	v_mfma_f32_16x16x32_bf16 v[116:119], v[168:171], v[200:203], v[116:119]
	v_mfma_f32_16x16x32_bf16 v[112:115], v[192:195], v[200:203], v[112:115]
	v_mfma_f32_16x16x32_bf16 v[100:103], v[168:171], v[208:211], v[100:103]
	v_mfma_f32_16x16x32_bf16 v[96:99], v[192:195], v[208:211], v[96:99]
	v_mfma_f32_16x16x32_bf16 v[84:87], v[168:171], v[216:219], v[84:87]
	v_mfma_f32_16x16x32_bf16 v[80:83], v[192:195], v[216:219], v[80:83]
	v_mfma_f32_16x16x32_bf16 v[68:71], v[168:171], v[224:227], v[68:71]
	v_mfma_f32_16x16x32_bf16 v[64:67], v[192:195], v[224:227], v[64:67]
	v_mfma_f32_16x16x32_bf16 v[116:119], v[172:175], v[204:207], v[116:119]
	v_mfma_f32_16x16x32_bf16 v[112:115], v[196:199], v[204:207], v[112:115]
	v_mfma_f32_16x16x32_bf16 v[100:103], v[172:175], v[212:215], v[100:103]
	v_mfma_f32_16x16x32_bf16 v[96:99], v[196:199], v[212:215], v[96:99]
	v_mfma_f32_16x16x32_bf16 v[84:87], v[172:175], v[220:223], v[84:87]
	v_mfma_f32_16x16x32_bf16 v[80:83], v[196:199], v[220:223], v[80:83]
	v_mfma_f32_16x16x32_bf16 v[68:71], v[172:175], v[228:231], v[68:71]
	v_mfma_f32_16x16x32_bf16 v[64:67], v[196:199], v[228:231], v[64:67]
	s_barrier
	s_add_i32 s68, s82, s0
	v_lshl_add_u64 v[150:151], s[78:79], 0, v[152:153]
	s_mov_b32 m0, s68
	ds_read_b128 v[200:203], v149 offset:16384
	ds_read_b128 v[204:207], v149 offset:17408
	ds_read_b128 v[208:211], v149 offset:18432
	ds_read_b128 v[212:215], v149 offset:19456
	ds_read_b128 v[216:219], v149 offset:20480
	ds_read_b128 v[220:223], v149 offset:21504
	ds_read_b128 v[224:227], v149 offset:22528
	ds_read_b128 v[228:231], v149 offset:23552
	global_load_lds_dwordx4 v[150:151], off
	s_add_i32 m0, s68, 0x2000
	s_add_u32 s68, s78, 0x80000
	v_lshl_add_u64 v[182:183], s[78:79], 0, v[128:129]
	s_addc_u32 s69, s79, 0
	s_add_i32 s82, s83, s0
	global_load_lds_dwordx4 v[182:183], off
	v_lshl_add_u64 v[184:185], s[68:69], 0, v[152:153]
	s_mov_b32 m0, s82
	v_lshl_add_u64 v[188:189], s[80:81], 0, v[130:131]
	global_load_lds_dwordx4 v[184:185], off
	v_lshl_add_u64 v[184:185], s[68:69], 0, v[128:129]
	s_add_i32 m0, s82, 0x2000
	s_nop 0
	global_load_lds_dwordx4 v[184:185], off
	v_lshl_add_u64 v[184:185], s[80:81], 0, v[132:133]
	s_mov_b32 m0, s14
	s_nop 0
	global_load_lds_dwordx4 v[184:185], off
	s_mov_b32 m0, s15
	s_nop 0
	global_load_lds_dwordx4 v[188:189], off
	s_waitcnt vmcnt(8)
	s_waitcnt lgkmcnt(0)
	s_barrier
; #define PG8_STAGE(bufoff, gbase, voff) do { _Pragma("unroll") for (int _i = 0; _i < 2; ++_i) \
;         __builtin_amdgcn_global_load_lds((const unsigned*)((const char*)(gbase) + (voff)[_i]), (PG8_LAS unsigned*)(lds + (bufoff) + ldsw + _i * 8192), 16, 0, 0); } while (0)
; #define PG8_LDA(dst, b, h) do { _Pragma("unroll") for (int m = 0; m < 4; ++m) _Pragma("unroll") for (int k = 0; k < 2; ++k) dst[m][k] = *(const PG8_LAS bf16x8*)(lds + PG8_SA(b, h) + aoff + m * 2048 + k * 1024); } while (0)
; #define PG8_LDB(dst, b, h) do { _Pragma("unroll") for (int n = 0; n < 2; ++n) _Pragma("unroll") for (int k = 0; k < 2; ++k) dst[n][k] = *(const PG8_LAS bf16x8*)(lds + PG8_SB(b, h) + boff + n * 2048 + k * 1024); } while (0)
; #define PG8_MMA(ai, bj, At, Bt) do { __builtin_amdgcn_s_setprio(1); _Pragma("unroll") for (int m = 0; m < 4; ++m) _Pragma("unroll") for (int n = 0; n < 2; ++n) _Pragma("unroll") for (int k = 0; k < 2; ++k) \
;         acc[ai][bj][m][n] = __builtin_amdgcn_mfma_f32_16x16x32_bf16(Bt[n][k], At[m][k], acc[ai][bj][m][n], 0, 0, 0); __builtin_amdgcn_s_setprio(0); } while (0)
; #define PG8_WAIT_V(n) asm volatile("s_waitcnt vmcnt(" #n ")" ::: "memory")
; #define PG8_WAIT_L(n) asm volatile("s_waitcnt lgkmcnt(" #n ")" ::: "memory")
; #define PG8_BAR __builtin_amdgcn_s_barrier()
; #define PG8_SCHED __builtin_amdgcn_sched_barrier(0)
; template <class Epi, class Sched, bool ALIGN_EPI = false, bool SP2 = false>
; __device__ __forceinline__ void gemm_phase(PG8_LAS unsigned char* lds, const Gemm g, const Sched& S, const Epi& E) {
;     ...
;             PG8_WAIT_V(8); PG8_WAIT_L(0); PG8_BAR; PG8_MMA(1, 0, At, B0); PG8_MMA(1, 1, At, B1); PG8_BAR; PG8_SCHED;
;             PG8_LDB(B0, 1, 0); PG8_LDB(B1, 1, 1); PG8_SCHED; PG8_LDA(At, 1, 0); PG8_STAGE(PG8_SA(0, 1), a2 + hstep, voffA);
;             PG8_WAIT_V(8); PG8_WAIT_L(0); PG8_BAR; PG8_MMA(0, 0, At, B0); PG8_MMA(0, 1, At, B1); PG8_BAR; PG8_SCHED;
;             PG8_LDA(At, 1, 1); PG8_STAGE(PG8_SB(1, 0), b3, voffB); PG8_STAGE(PG8_SB(1, 1), b3 + hstep, voffB); PG8_STAGE(PG8_SA(1, 0), a3, voffA);
	v_mfma_f32_16x16x32_bf16 v[60:63], v[140:143], v[200:203], v[60:63]
	v_mfma_f32_16x16x32_bf16 v[56:59], v[160:163], v[200:203], v[56:59]
	v_mfma_f32_16x16x32_bf16 v[44:47], v[140:143], v[208:211], v[44:47]
	v_mfma_f32_16x16x32_bf16 v[40:43], v[160:163], v[208:211], v[40:43]
	v_mfma_f32_16x16x32_bf16 v[28:31], v[140:143], v[216:219], v[28:31]
	v_mfma_f32_16x16x32_bf16 v[24:27], v[160:163], v[216:219], v[24:27]
	v_mfma_f32_16x16x32_bf16 v[12:15], v[140:143], v[224:227], v[12:15]
	v_mfma_f32_16x16x32_bf16 v[8:11], v[160:163], v[224:227], v[8:11]
	v_mfma_f32_16x16x32_bf16 v[60:63], v[156:159], v[204:207], v[60:63]
	v_mfma_f32_16x16x32_bf16 v[56:59], v[164:167], v[204:207], v[56:59]
	v_mfma_f32_16x16x32_bf16 v[44:47], v[156:159], v[212:215], v[44:47]
	v_mfma_f32_16x16x32_bf16 v[40:43], v[164:167], v[212:215], v[40:43]
	v_mfma_f32_16x16x32_bf16 v[28:31], v[156:159], v[220:223], v[28:31]
	v_mfma_f32_16x16x32_bf16 v[24:27], v[164:167], v[220:223], v[24:27]
	v_mfma_f32_16x16x32_bf16 v[12:15], v[156:159], v[228:231], v[12:15]
	v_mfma_f32_16x16x32_bf16 v[8:11], v[164:167], v[228:231], v[8:11]
	v_mfma_f32_16x16x32_bf16 v[52:55], v[168:171], v[200:203], v[52:55]
	v_mfma_f32_16x16x32_bf16 v[48:51], v[192:195], v[200:203], v[48:51]
	v_mfma_f32_16x16x32_bf16 v[36:39], v[168:171], v[208:211], v[36:39]
	v_mfma_f32_16x16x32_bf16 v[32:35], v[192:195], v[208:211], v[32:35]
	v_mfma_f32_16x16x32_bf16 v[20:23], v[168:171], v[216:219], v[20:23]
	v_mfma_f32_16x16x32_bf16 v[16:19], v[192:195], v[216:219], v[16:19]
	v_mfma_f32_16x16x32_bf16 v[4:7], v[168:171], v[224:227], v[4:7]
	v_mfma_f32_16x16x32_bf16 v[0:3], v[192:195], v[224:227], v[0:3]
	v_mfma_f32_16x16x32_bf16 v[52:55], v[172:175], v[204:207], v[52:55]
	v_mfma_f32_16x16x32_bf16 v[48:51], v[196:199], v[204:207], v[48:51]
	v_mfma_f32_16x16x32_bf16 v[36:39], v[172:175], v[212:215], v[36:39]
	v_mfma_f32_16x16x32_bf16 v[32:35], v[196:199], v[212:215], v[32:35]
	v_mfma_f32_16x16x32_bf16 v[20:23], v[172:175], v[220:223], v[20:23]
	v_mfma_f32_16x16x32_bf16 v[16:19], v[196:199], v[220:223], v[16:19]
	v_mfma_f32_16x16x32_bf16 v[4:7], v[172:175], v[228:231], v[4:7]
	v_mfma_f32_16x16x32_bf16 v[0:3], v[196:199], v[228:231], v[0:3]
	s_barrier
	v_add_u32_e32 v144, s93, v147
	s_add_i32 s82, 0, 0x1c000
	ds_read_b128 v[140:143], v144
	ds_read_b128 v[156:159], v144 offset:1024
	ds_read_b128 v[160:163], v144 offset:2048
	ds_read_b128 v[164:167], v144 offset:3072
	v_add_u32_e32 v144, s82, v147
	ds_read_b128 v[168:171], v144
	ds_read_b128 v[172:175], v144 offset:1024
	ds_read_b128 v[192:195], v144 offset:2048
	ds_read_b128 v[196:199], v144 offset:3072
	s_add_u32 s68, s80, 0x80000
	s_addc_u32 s69, s81, 0
	s_mov_b32 m0, s16
	v_lshl_add_u64 v[190:191], s[68:69], 0, v[132:133]
	ds_read_b128 v[200:203], v149 offset:32768
	ds_read_b128 v[204:207], v149 offset:33792
	ds_read_b128 v[208:211], v149 offset:34816
	ds_read_b128 v[212:215], v149 offset:35840
	ds_read_b128 v[216:219], v149 offset:36864
	ds_read_b128 v[220:223], v149 offset:37888
	ds_read_b128 v[224:227], v149 offset:38912
	ds_read_b128 v[228:231], v149 offset:39936
	global_load_lds_dwordx4 v[190:191], off
	v_lshl_add_u64 v[190:191], s[68:69], 0, v[130:131]
	s_mov_b32 m0, s17
	s_nop 0
	global_load_lds_dwordx4 v[190:191], off
	s_waitcnt vmcnt(8)
	s_waitcnt lgkmcnt(0)
	s_barrier
	v_mfma_f32_16x16x32_bf16 v[124:127], v[140:143], v[200:203], v[124:127]
	v_mfma_f32_16x16x32_bf16 v[120:123], v[160:163], v[200:203], v[120:123]
	v_mfma_f32_16x16x32_bf16 v[108:111], v[140:143], v[208:211], v[108:111]
	v_mfma_f32_16x16x32_bf16 v[104:107], v[160:163], v[208:211], v[104:107]
	v_mfma_f32_16x16x32_bf16 v[92:95], v[140:143], v[216:219], v[92:95]
	v_mfma_f32_16x16x32_bf16 v[88:91], v[160:163], v[216:219], v[88:91]
	v_mfma_f32_16x16x32_bf16 v[76:79], v[140:143], v[224:227], v[76:79]
	v_mfma_f32_16x16x32_bf16 v[72:75], v[160:163], v[224:227], v[72:75]
	v_mfma_f32_16x16x32_bf16 v[124:127], v[156:159], v[204:207], v[124:127]
	v_mfma_f32_16x16x32_bf16 v[120:123], v[164:167], v[204:207], v[120:123]
	v_mfma_f32_16x16x32_bf16 v[108:111], v[156:159], v[212:215], v[108:111]
	v_mfma_f32_16x16x32_bf16 v[104:107], v[164:167], v[212:215], v[104:107]
	v_mfma_f32_16x16x32_bf16 v[92:95], v[156:159], v[220:223], v[92:95]
	v_mfma_f32_16x16x32_bf16 v[88:91], v[164:167], v[220:223], v[88:91]
	v_mfma_f32_16x16x32_bf16 v[76:79], v[156:159], v[228:231], v[76:79]
	v_mfma_f32_16x16x32_bf16 v[72:75], v[164:167], v[228:231], v[72:75]
	v_mfma_f32_16x16x32_bf16 v[116:119], v[168:171], v[200:203], v[116:119]
	v_mfma_f32_16x16x32_bf16 v[112:115], v[192:195], v[200:203], v[112:115]
	v_mfma_f32_16x16x32_bf16 v[100:103], v[168:171], v[208:211], v[100:103]
	v_mfma_f32_16x16x32_bf16 v[96:99], v[192:195], v[208:211], v[96:99]
	v_mfma_f32_16x16x32_bf16 v[84:87], v[168:171], v[216:219], v[84:87]
	v_mfma_f32_16x16x32_bf16 v[80:83], v[192:195], v[216:219], v[80:83]
	v_mfma_f32_16x16x32_bf16 v[68:71], v[168:171], v[224:227], v[68:71]
	v_mfma_f32_16x16x32_bf16 v[64:67], v[192:195], v[224:227], v[64:67]
	v_mfma_f32_16x16x32_bf16 v[116:119], v[172:175], v[204:207], v[116:119]
	v_mfma_f32_16x16x32_bf16 v[112:115], v[196:199], v[204:207], v[112:115]
	v_mfma_f32_16x16x32_bf16 v[100:103], v[172:175], v[212:215], v[100:103]
	v_mfma_f32_16x16x32_bf16 v[96:99], v[196:199], v[212:215], v[96:99]
	v_mfma_f32_16x16x32_bf16 v[84:87], v[172:175], v[220:223], v[84:87]
	v_mfma_f32_16x16x32_bf16 v[80:83], v[196:199], v[220:223], v[80:83]
	v_mfma_f32_16x16x32_bf16 v[68:71], v[172:175], v[228:231], v[68:71]
	v_mfma_f32_16x16x32_bf16 v[64:67], v[196:199], v[228:231], v[64:67]
	s_barrier
; #define PG8_STAGE(bufoff, gbase, voff) do { _Pragma("unroll") for (int _i = 0; _i < 2; ++_i) \
;         __builtin_amdgcn_global_load_lds((const unsigned*)((const char*)(gbase) + (voff)[_i]), (PG8_LAS unsigned*)(lds + (bufoff) + ldsw + _i * 8192), 16, 0, 0); } while (0)
; #define PG8_LDA(dst, b, h) do { _Pragma("unroll") for (int m = 0; m < 4; ++m) _Pragma("unroll") for (int k = 0; k < 2; ++k) dst[m][k] = *(const PG8_LAS bf16x8*)(lds + PG8_SA(b, h) + aoff + m * 2048 + k * 1024); } while (0)
; #define PG8_MMA(ai, bj, At, Bt) do { __builtin_amdgcn_s_setprio(1); _Pragma("unroll") for (int m = 0; m < 4; ++m) _Pragma("unroll") for (int n = 0; n < 2; ++n) _Pragma("unroll") for (int k = 0; k < 2; ++k) \
;         acc[ai][bj][m][n] = __builtin_amdgcn_mfma_f32_16x16x32_bf16(Bt[n][k], At[m][k], acc[ai][bj][m][n], 0, 0, 0); __builtin_amdgcn_s_setprio(0); } while (0)
; #define PG8_WAIT_V(n) asm volatile("s_waitcnt vmcnt(" #n ")" ::: "memory")
; #define PG8_WAIT_L(n) asm volatile("s_waitcnt lgkmcnt(" #n ")" ::: "memory")
; #define PG8_BAR __builtin_amdgcn_s_barrier()
; #define PG8_SCHED __builtin_amdgcn_sched_barrier(0)
; template <class Epi, class Sched, bool ALIGN_EPI = false, bool SP2 = false>
; __device__ __forceinline__ void gemm_phase(PG8_LAS unsigned char* lds, const Gemm g, const Sched& S, const Epi& E) {
;     ...
;         for (int t = 0; t < nt; t += 2) {
;     ...
;             PG8_LDA(At, 1, 1); PG8_STAGE(PG8_SB(1, 0), b3, voffB); PG8_STAGE(PG8_SB(1, 1), b3 + hstep, voffB); PG8_STAGE(PG8_SA(1, 0), a3, voffA);
;             PG8_WAIT_V(8); PG8_WAIT_L(0); PG8_BAR; PG8_MMA(1, 0, At, B0); PG8_MMA(1, 1, At, B1); PG8_BAR; PG8_SCHED;
	s_add_i32 s68, s93, s0
	v_lshl_add_u64 v[150:151], v[150:151], 0, s[18:19]
	s_mov_b32 m0, s68
	ds_read_b128 v[200:203], v149 offset:49152
	ds_read_b128 v[204:207], v149 offset:50176
	ds_read_b128 v[208:211], v149 offset:51200
	ds_read_b128 v[212:215], v149 offset:52224
	ds_read_b128 v[216:219], v149 offset:53248
	ds_read_b128 v[220:223], v149 offset:54272
	ds_read_b128 v[224:227], v149 offset:55296
	ds_read_b128 v[228:231], v149 offset:56320
	global_load_lds_dwordx4 v[150:151], off
	s_add_i32 m0, s68, 0x2000
	s_add_u32 s68, s78, 0x80080
	v_lshl_add_u64 v[150:151], v[182:183], 0, s[18:19]
	s_addc_u32 s69, s79, 0
	s_add_i32 s78, s82, s0
	global_load_lds_dwordx4 v[150:151], off
	v_lshl_add_u64 v[150:151], s[68:69], 0, v[152:153]
	s_mov_b32 m0, s78
	s_nop 0
	global_load_lds_dwordx4 v[150:151], off
	v_lshl_add_u64 v[150:151], s[68:69], 0, v[128:129]
	s_add_i32 m0, s78, 0x2000
	s_nop 0
	global_load_lds_dwordx4 v[150:151], off
	v_lshl_add_u64 v[150:151], v[184:185], 0, s[18:19]
	s_mov_b32 m0, s22
	s_nop 0
	global_load_lds_dwordx4 v[150:151], off
	v_lshl_add_u64 v[150:151], v[188:189], 0, s[18:19]
	s_mov_b32 m0, s23
	s_nop 0
	global_load_lds_dwordx4 v[150:151], off
	s_waitcnt vmcnt(8)
	s_waitcnt lgkmcnt(0)
	s_barrier
	v_mfma_f32_16x16x32_bf16 v[60:63], v[140:143], v[200:203], v[60:63]
	v_mfma_f32_16x16x32_bf16 v[56:59], v[160:163], v[200:203], v[56:59]
	v_mfma_f32_16x16x32_bf16 v[44:47], v[140:143], v[208:211], v[44:47]
	v_mfma_f32_16x16x32_bf16 v[40:43], v[160:163], v[208:211], v[40:43]
	v_mfma_f32_16x16x32_bf16 v[28:31], v[140:143], v[216:219], v[28:31]
	v_mfma_f32_16x16x32_bf16 v[24:27], v[160:163], v[216:219], v[24:27]
	v_mfma_f32_16x16x32_bf16 v[12:15], v[140:143], v[224:227], v[12:15]
	v_mfma_f32_16x16x32_bf16 v[8:11], v[160:163], v[224:227], v[8:11]
	v_mfma_f32_16x16x32_bf16 v[60:63], v[156:159], v[204:207], v[60:63]
	v_mfma_f32_16x16x32_bf16 v[56:59], v[164:167], v[204:207], v[56:59]
	v_mfma_f32_16x16x32_bf16 v[44:47], v[156:159], v[212:215], v[44:47]
	v_mfma_f32_16x16x32_bf16 v[40:43], v[164:167], v[212:215], v[40:43]
	v_mfma_f32_16x16x32_bf16 v[28:31], v[156:159], v[220:223], v[28:31]
	v_mfma_f32_16x16x32_bf16 v[24:27], v[164:167], v[220:223], v[24:27]
	v_mfma_f32_16x16x32_bf16 v[12:15], v[156:159], v[228:231], v[12:15]
	v_mfma_f32_16x16x32_bf16 v[8:11], v[164:167], v[228:231], v[8:11]
	v_mfma_f32_16x16x32_bf16 v[52:55], v[168:171], v[200:203], v[52:55]
	v_mfma_f32_16x16x32_bf16 v[48:51], v[192:195], v[200:203], v[48:51]
	v_mfma_f32_16x16x32_bf16 v[36:39], v[168:171], v[208:211], v[36:39]
	v_mfma_f32_16x16x32_bf16 v[32:35], v[192:195], v[208:211], v[32:35]
	v_mfma_f32_16x16x32_bf16 v[20:23], v[168:171], v[216:219], v[20:23]
	v_mfma_f32_16x16x32_bf16 v[16:19], v[192:195], v[216:219], v[16:19]
	v_mfma_f32_16x16x32_bf16 v[4:7], v[168:171], v[224:227], v[4:7]
	v_mfma_f32_16x16x32_bf16 v[0:3], v[192:195], v[224:227], v[0:3]
	v_mfma_f32_16x16x32_bf16 v[52:55], v[172:175], v[204:207], v[52:55]
	v_mfma_f32_16x16x32_bf16 v[48:51], v[196:199], v[204:207], v[48:51]
	v_mfma_f32_16x16x32_bf16 v[36:39], v[172:175], v[212:215], v[36:39]
	v_mfma_f32_16x16x32_bf16 v[32:35], v[196:199], v[212:215], v[32:35]
	v_mfma_f32_16x16x32_bf16 v[20:23], v[172:175], v[220:223], v[20:23]
	v_mfma_f32_16x16x32_bf16 v[16:19], v[196:199], v[220:223], v[16:19]
	v_mfma_f32_16x16x32_bf16 v[4:7], v[172:175], v[228:231], v[4:7]
	v_mfma_f32_16x16x32_bf16 v[0:3], v[196:199], v[228:231], v[0:3]
	s_barrier
	s_add_i32 s71, s71, 2
	s_add_u32 s42, s42, 0x100
	s_addc_u32 s43, s43, 0
	s_add_u32 s59, s59, 0x100
	s_addc_u32 s63, s63, 0
	s_cmp_gt_u32 s71, 29
	s_cbranch_scc0 .LBB0_165
	s_and_b64 vcc, exec, s[24:25]
	s_cbranch_vccz .LBB0_168
	s_barrier

; #define PG8_STAGE(bufoff, gbase, voff) do { _Pragma("unroll") for (int _i = 0; _i < 2; ++_i) \
;         __builtin_amdgcn_global_load_lds((const unsigned*)((const char*)(gbase) + (voff)[_i]), (PG8_LAS unsigned*)(lds + (bufoff) + ldsw + _i * 8192), 16, 0, 0); } while (0)
; #define PG8_LDA(dst, b, h) do { _Pragma("unroll") for (int m = 0; m < 4; ++m) _Pragma("unroll") for (int k = 0; k < 2; ++k) dst[m][k] = *(const PG8_LAS bf16x8*)(lds + PG8_SA(b, h) + aoff + m * 2048 + k * 1024); } while (0)
; #define PG8_LDB(dst, b, h) do { _Pragma("unroll") for (int n = 0; n < 2; ++n) _Pragma("unroll") for (int k = 0; k < 2; ++k) dst[n][k] = *(const PG8_LAS bf16x8*)(lds + PG8_SB(b, h) + boff + n * 2048 + k * 1024); } while (0)
; #define PG8_MMA(ai, bj, At, Bt) do { __builtin_amdgcn_s_setprio(1); _Pragma("unroll") for (int m = 0; m < 4; ++m) _Pragma("unroll") for (int n = 0; n < 2; ++n) _Pragma("unroll") for (int k = 0; k < 2; ++k) \
;         acc[ai][bj][m][n] = __builtin_amdgcn_mfma_f32_16x16x32_bf16(Bt[n][k], At[m][k], acc[ai][bj][m][n], 0, 0, 0); __builtin_amdgcn_s_setprio(0); } while (0)
; #define PG8_WAIT_V(n) asm volatile("s_waitcnt vmcnt(" #n ")" ::: "memory")
; #define PG8_WAIT_L(n) asm volatile("s_waitcnt lgkmcnt(" #n ")" ::: "memory")
; #define PG8_BAR __builtin_amdgcn_s_barrier()
; #define PG8_SCHED __builtin_amdgcn_sched_barrier(0)
; template <class Epi, class Sched, bool ALIGN_EPI = false, bool SP2 = false>
; __device__ __forceinline__ void gemm_phase(PG8_LAS unsigned char* lds, const Gemm g, const Sched& S, const Epi& E) {
;     ...
;             PG8_LDB(B0, 0, 0); PG8_LDB(B1, 0, 1); PG8_SCHED; PG8_LDA(At, 0, 0); PG8_STAGE(PG8_SA(1, 1), a1 + hstep, voffA);
;             PG8_WAIT_V(8); PG8_WAIT_L(0); PG8_BAR; PG8_MMA(0, 0, At, B0); PG8_MMA(0, 1, At, B1); PG8_BAR; PG8_SCHED;
;             PG8_LDA(At, 0, 1); PG8_STAGE(PG8_SB(0, 0), b2, voffB); PG8_STAGE(PG8_SB(0, 1), b2 + hstep, voffB); PG8_STAGE(PG8_SA(0, 0), a2, voffA);
.LBB0_218:
	s_add_i32 vcc_lo, s46, 2
	s_add_u32 s68, s44, 0x80
	s_addc_u32 s47, s45, 0
	s_add_i32 vcc_hi, 0, 0x10000
	s_cmp_eq_u32 s15, s46
	s_cselect_b32 s47, s83, s47
	s_cselect_b32 s46, s82, s68
	v_add_u32_e32 v146, vcc_hi, v149
	s_cselect_b32 s69, s85, s87
	s_cselect_b32 s68, s84, s86
	s_add_i32 s96, 0, 0x14000
	ds_read_b128 v[138:141], v146
	ds_read_b128 v[142:145], v146 offset:1024
	ds_read_b128 v[156:159], v146 offset:2048
	ds_read_b128 v[160:163], v146 offset:3072
	v_add_u32_e32 v146, s96, v149
	ds_read_b128 v[164:167], v146
	ds_read_b128 v[168:171], v146 offset:1024
	ds_read_b128 v[172:175], v146 offset:2048
	ds_read_b128 v[192:195], v146 offset:3072
	v_lshl_add_u64 v[146:147], s[44:45], 0, v[134:135]
	s_add_i32 m0, s54, 0xc000
	ds_read_b128 v[196:199], v151
	ds_read_b128 v[200:203], v151 offset:1024
	ds_read_b128 v[204:207], v151 offset:2048
	ds_read_b128 v[208:211], v151 offset:3072
	ds_read_b128 v[212:215], v151 offset:4096
	ds_read_b128 v[216:219], v151 offset:5120
	ds_read_b128 v[220:223], v151 offset:6144
	ds_read_b128 v[224:227], v151 offset:7168
	global_load_lds_dwordx4 v[146:147], off
	v_lshl_add_u64 v[146:147], s[44:45], 0, v[136:137]
	s_add_i32 m0, s54, 0xe000
	s_nop 0
	global_load_lds_dwordx4 v[146:147], off
	s_waitcnt vmcnt(8)
	s_waitcnt lgkmcnt(0)
	s_barrier
	v_mfma_f32_16x16x32_bf16 v[124:127], v[138:141], v[196:199], v[124:127]
	v_mfma_f32_16x16x32_bf16 v[120:123], v[156:159], v[196:199], v[120:123]
	v_mfma_f32_16x16x32_bf16 v[108:111], v[138:141], v[204:207], v[108:111]
	v_mfma_f32_16x16x32_bf16 v[104:107], v[156:159], v[204:207], v[104:107]
	v_mfma_f32_16x16x32_bf16 v[92:95], v[138:141], v[212:215], v[92:95]
	v_mfma_f32_16x16x32_bf16 v[88:91], v[156:159], v[212:215], v[88:91]
	v_mfma_f32_16x16x32_bf16 v[76:79], v[138:141], v[220:223], v[76:79]
	v_mfma_f32_16x16x32_bf16 v[72:75], v[156:159], v[220:223], v[72:75]
	v_mfma_f32_16x16x32_bf16 v[124:127], v[142:145], v[200:203], v[124:127]
	v_mfma_f32_16x16x32_bf16 v[120:123], v[160:163], v[200:203], v[120:123]
	v_mfma_f32_16x16x32_bf16 v[108:111], v[142:145], v[208:211], v[108:111]
	v_mfma_f32_16x16x32_bf16 v[104:107], v[160:163], v[208:211], v[104:107]
	v_mfma_f32_16x16x32_bf16 v[92:95], v[142:145], v[216:219], v[92:95]
	v_mfma_f32_16x16x32_bf16 v[88:91], v[160:163], v[216:219], v[88:91]
	v_mfma_f32_16x16x32_bf16 v[76:79], v[142:145], v[224:227], v[76:79]
	v_mfma_f32_16x16x32_bf16 v[72:75], v[160:163], v[224:227], v[72:75]
	v_mfma_f32_16x16x32_bf16 v[116:119], v[164:167], v[196:199], v[116:119]
	v_mfma_f32_16x16x32_bf16 v[112:115], v[172:175], v[196:199], v[112:115]
	v_mfma_f32_16x16x32_bf16 v[100:103], v[164:167], v[204:207], v[100:103]
	v_mfma_f32_16x16x32_bf16 v[96:99], v[172:175], v[204:207], v[96:99]
	v_mfma_f32_16x16x32_bf16 v[84:87], v[164:167], v[212:215], v[84:87]
	v_mfma_f32_16x16x32_bf16 v[80:83], v[172:175], v[212:215], v[80:83]
	v_mfma_f32_16x16x32_bf16 v[68:71], v[164:167], v[220:223], v[68:71]
	v_mfma_f32_16x16x32_bf16 v[64:67], v[172:175], v[220:223], v[64:67]
	v_mfma_f32_16x16x32_bf16 v[116:119], v[168:171], v[200:203], v[116:119]
	v_mfma_f32_16x16x32_bf16 v[112:115], v[192:195], v[200:203], v[112:115]
	v_mfma_f32_16x16x32_bf16 v[100:103], v[168:171], v[208:211], v[100:103]
	v_mfma_f32_16x16x32_bf16 v[96:99], v[192:195], v[208:211], v[96:99]
	v_mfma_f32_16x16x32_bf16 v[84:87], v[168:171], v[216:219], v[84:87]
	v_mfma_f32_16x16x32_bf16 v[80:83], v[192:195], v[216:219], v[80:83]
	v_mfma_f32_16x16x32_bf16 v[68:71], v[168:171], v[224:227], v[68:71]
	v_mfma_f32_16x16x32_bf16 v[64:67], v[192:195], v[224:227], v[64:67]
	s_barrier
	s_add_i32 vcc_hi, vcc_hi, s63
	v_lshl_add_u64 v[146:147], s[68:69], 0, v[152:153]
	s_mov_b32 m0, vcc_hi
	ds_read_b128 v[196:199], v151 offset:16384
	ds_read_b128 v[200:203], v151 offset:17408
	ds_read_b128 v[204:207], v151 offset:18432
	ds_read_b128 v[208:211], v151 offset:19456
	ds_read_b128 v[212:215], v151 offset:20480
	ds_read_b128 v[216:219], v151 offset:21504
	ds_read_b128 v[220:223], v151 offset:22528
	ds_read_b128 v[224:227], v151 offset:23552
	global_load_lds_dwordx4 v[146:147], off
	s_add_i32 m0, vcc_hi, 0x2000
	v_lshl_add_u64 v[182:183], s[68:69], 0, v[128:129]
	s_add_u32 s68, s68, s48
	s_addc_u32 s69, s69, 0
	s_add_i32 s96, s96, s63
	global_load_lds_dwordx4 v[182:183], off
	v_lshl_add_u64 v[184:185], s[68:69], 0, v[152:153]
	s_mov_b32 m0, s96
	v_lshl_add_u64 v[188:189], s[68:69], 0, v[128:129]
	global_load_lds_dwordx4 v[184:185], off
	s_add_i32 m0, s96, 0x2000
	v_lshl_add_u64 v[190:191], s[46:47], 0, v[132:133]
	global_load_lds_dwordx4 v[188:189], off
	s_mov_b32 m0, s54
	v_lshl_add_u64 v[228:229], s[46:47], 0, v[130:131]
	global_load_lds_dwordx4 v[190:191], off
	s_mov_b32 m0, s55
	s_nop 0
	global_load_lds_dwordx4 v[228:229], off
	s_waitcnt vmcnt(8)
	s_waitcnt lgkmcnt(0)
	s_barrier
; #define PG8_STAGE(bufoff, gbase, voff) do { _Pragma("unroll") for (int _i = 0; _i < 2; ++_i) \
;         __builtin_amdgcn_global_load_lds((const unsigned*)((const char*)(gbase) + (voff)[_i]), (PG8_LAS unsigned*)(lds + (bufoff) + ldsw + _i * 8192), 16, 0, 0); } while (0)
; #define PG8_LDA(dst, b, h) do { _Pragma("unroll") for (int m = 0; m < 4; ++m) _Pragma("unroll") for (int k = 0; k < 2; ++k) dst[m][k] = *(const PG8_LAS bf16x8*)(lds + PG8_SA(b, h) + aoff + m * 2048 + k * 1024); } while (0)
; #define PG8_LDB(dst, b, h) do { _Pragma("unroll") for (int n = 0; n < 2; ++n) _Pragma("unroll") for (int k = 0; k < 2; ++k) dst[n][k] = *(const PG8_LAS bf16x8*)(lds + PG8_SB(b, h) + boff + n * 2048 + k * 1024); } while (0)
; #define PG8_MMA(ai, bj, At, Bt) do { __builtin_amdgcn_s_setprio(1); _Pragma("unroll") for (int m = 0; m < 4; ++m) _Pragma("unroll") for (int n = 0; n < 2; ++n) _Pragma("unroll") for (int k = 0; k < 2; ++k) \
;         acc[ai][bj][m][n] = __builtin_amdgcn_mfma_f32_16x16x32_bf16(Bt[n][k], At[m][k], acc[ai][bj][m][n], 0, 0, 0); __builtin_amdgcn_s_setprio(0); } while (0)
; #define PG8_WAIT_V(n) asm volatile("s_waitcnt vmcnt(" #n ")" ::: "memory")
; #define PG8_WAIT_L(n) asm volatile("s_waitcnt lgkmcnt(" #n ")" ::: "memory")
; #define PG8_BAR __builtin_amdgcn_s_barrier()
; #define PG8_SCHED __builtin_amdgcn_sched_barrier(0)
; template <class Epi, class Sched, bool ALIGN_EPI = false, bool SP2 = false>
; __device__ __forceinline__ void gemm_phase(PG8_LAS unsigned char* lds, const Gemm g, const Sched& S, const Epi& E) {
;     ...
;             PG8_WAIT_V(8); PG8_WAIT_L(0); PG8_BAR; PG8_MMA(1, 0, At, B0); PG8_MMA(1, 1, At, B1); PG8_BAR; PG8_SCHED;
;             PG8_LDB(B0, 1, 0); PG8_LDB(B1, 1, 1); PG8_SCHED; PG8_LDA(At, 1, 0); PG8_STAGE(PG8_SA(0, 1), a2 + hstep, voffA);
;             PG8_WAIT_V(8); PG8_WAIT_L(0); PG8_BAR; PG8_MMA(0, 0, At, B0); PG8_MMA(0, 1, At, B1); PG8_BAR; PG8_SCHED;
;             PG8_LDA(At, 1, 1); PG8_STAGE(PG8_SB(1, 0), b3, voffB); PG8_STAGE(PG8_SB(1, 1), b3 + hstep, voffB); PG8_STAGE(PG8_SA(1, 0), a3, voffA);
	v_mfma_f32_16x16x32_bf16 v[60:63], v[138:141], v[196:199], v[60:63]
	v_mfma_f32_16x16x32_bf16 v[56:59], v[156:159], v[196:199], v[56:59]
	v_mfma_f32_16x16x32_bf16 v[44:47], v[138:141], v[204:207], v[44:47]
	v_mfma_f32_16x16x32_bf16 v[40:43], v[156:159], v[204:207], v[40:43]
	v_mfma_f32_16x16x32_bf16 v[28:31], v[138:141], v[212:215], v[28:31]
	v_mfma_f32_16x16x32_bf16 v[24:27], v[156:159], v[212:215], v[24:27]
	v_mfma_f32_16x16x32_bf16 v[12:15], v[138:141], v[220:223], v[12:15]
	v_mfma_f32_16x16x32_bf16 v[8:11], v[156:159], v[220:223], v[8:11]
	v_mfma_f32_16x16x32_bf16 v[60:63], v[142:145], v[200:203], v[60:63]
	v_mfma_f32_16x16x32_bf16 v[56:59], v[160:163], v[200:203], v[56:59]
	v_mfma_f32_16x16x32_bf16 v[44:47], v[142:145], v[208:211], v[44:47]
	v_mfma_f32_16x16x32_bf16 v[40:43], v[160:163], v[208:211], v[40:43]
	v_mfma_f32_16x16x32_bf16 v[28:31], v[142:145], v[216:219], v[28:31]
	v_mfma_f32_16x16x32_bf16 v[24:27], v[160:163], v[216:219], v[24:27]
	v_mfma_f32_16x16x32_bf16 v[12:15], v[142:145], v[224:227], v[12:15]
	v_mfma_f32_16x16x32_bf16 v[8:11], v[160:163], v[224:227], v[8:11]
	v_mfma_f32_16x16x32_bf16 v[52:55], v[164:167], v[196:199], v[52:55]
	v_mfma_f32_16x16x32_bf16 v[48:51], v[172:175], v[196:199], v[48:51]
	v_mfma_f32_16x16x32_bf16 v[36:39], v[164:167], v[204:207], v[36:39]
	v_mfma_f32_16x16x32_bf16 v[32:35], v[172:175], v[204:207], v[32:35]
	v_mfma_f32_16x16x32_bf16 v[20:23], v[164:167], v[212:215], v[20:23]
	v_mfma_f32_16x16x32_bf16 v[16:19], v[172:175], v[212:215], v[16:19]
	v_mfma_f32_16x16x32_bf16 v[4:7], v[164:167], v[220:223], v[4:7]
	v_mfma_f32_16x16x32_bf16 v[0:3], v[172:175], v[220:223], v[0:3]
	v_mfma_f32_16x16x32_bf16 v[52:55], v[168:171], v[200:203], v[52:55]
	v_mfma_f32_16x16x32_bf16 v[48:51], v[192:195], v[200:203], v[48:51]
	v_mfma_f32_16x16x32_bf16 v[36:39], v[168:171], v[208:211], v[36:39]
	v_mfma_f32_16x16x32_bf16 v[32:35], v[192:195], v[208:211], v[32:35]
	v_mfma_f32_16x16x32_bf16 v[20:23], v[168:171], v[216:219], v[20:23]
	v_mfma_f32_16x16x32_bf16 v[16:19], v[192:195], v[216:219], v[16:19]
	v_mfma_f32_16x16x32_bf16 v[4:7], v[168:171], v[224:227], v[4:7]
	v_mfma_f32_16x16x32_bf16 v[0:3], v[192:195], v[224:227], v[0:3]
	s_barrier
	v_add_u32_e32 v155, s93, v149
	s_add_i32 s68, 0, 0x1c000
	ds_read_b128 v[138:141], v155
	ds_read_b128 v[142:145], v155 offset:1024
	ds_read_b128 v[156:159], v155 offset:2048
	ds_read_b128 v[160:163], v155 offset:3072
	v_add_u32_e32 v155, s68, v149
	ds_read_b128 v[164:167], v155
	ds_read_b128 v[168:171], v155 offset:1024
	ds_read_b128 v[172:175], v155 offset:2048
	ds_read_b128 v[192:195], v155 offset:3072
	s_add_u32 s46, s46, s48
	s_addc_u32 s47, s47, 0
	s_mov_b32 m0, s34
	v_lshl_add_u64 v[230:231], s[46:47], 0, v[132:133]
	ds_read_b128 v[196:199], v151 offset:32768
	ds_read_b128 v[200:203], v151 offset:33792
	ds_read_b128 v[204:207], v151 offset:34816
	ds_read_b128 v[208:211], v151 offset:35840
	ds_read_b128 v[212:215], v151 offset:36864
	ds_read_b128 v[216:219], v151 offset:37888
	ds_read_b128 v[220:223], v151 offset:38912
	ds_read_b128 v[224:227], v151 offset:39936
	global_load_lds_dwordx4 v[230:231], off
	v_lshl_add_u64 v[230:231], s[46:47], 0, v[130:131]
	s_mov_b32 m0, s95
	s_nop 0
	global_load_lds_dwordx4 v[230:231], off
	s_waitcnt vmcnt(8)
	s_waitcnt lgkmcnt(0)
	s_barrier
	v_mfma_f32_16x16x32_bf16 v[124:127], v[138:141], v[196:199], v[124:127]
	v_mfma_f32_16x16x32_bf16 v[120:123], v[156:159], v[196:199], v[120:123]
	v_mfma_f32_16x16x32_bf16 v[108:111], v[138:141], v[204:207], v[108:111]
	v_mfma_f32_16x16x32_bf16 v[104:107], v[156:159], v[204:207], v[104:107]
	v_mfma_f32_16x16x32_bf16 v[92:95], v[138:141], v[212:215], v[92:95]
	v_mfma_f32_16x16x32_bf16 v[88:91], v[156:159], v[212:215], v[88:91]
	v_mfma_f32_16x16x32_bf16 v[76:79], v[138:141], v[220:223], v[76:79]
	v_mfma_f32_16x16x32_bf16 v[72:75], v[156:159], v[220:223], v[72:75]
	v_mfma_f32_16x16x32_bf16 v[124:127], v[142:145], v[200:203], v[124:127]
	v_mfma_f32_16x16x32_bf16 v[120:123], v[160:163], v[200:203], v[120:123]
	v_mfma_f32_16x16x32_bf16 v[108:111], v[142:145], v[208:211], v[108:111]
	v_mfma_f32_16x16x32_bf16 v[104:107], v[160:163], v[208:211], v[104:107]
	v_mfma_f32_16x16x32_bf16 v[92:95], v[142:145], v[216:219], v[92:95]
	v_mfma_f32_16x16x32_bf16 v[88:91], v[160:163], v[216:219], v[88:91]
	v_mfma_f32_16x16x32_bf16 v[76:79], v[142:145], v[224:227], v[76:79]
	v_mfma_f32_16x16x32_bf16 v[72:75], v[160:163], v[224:227], v[72:75]
	v_mfma_f32_16x16x32_bf16 v[116:119], v[164:167], v[196:199], v[116:119]
	v_mfma_f32_16x16x32_bf16 v[112:115], v[172:175], v[196:199], v[112:115]
	v_mfma_f32_16x16x32_bf16 v[100:103], v[164:167], v[204:207], v[100:103]
	v_mfma_f32_16x16x32_bf16 v[96:99], v[172:175], v[204:207], v[96:99]
	v_mfma_f32_16x16x32_bf16 v[84:87], v[164:167], v[212:215], v[84:87]
	v_mfma_f32_16x16x32_bf16 v[80:83], v[172:175], v[212:215], v[80:83]
	v_mfma_f32_16x16x32_bf16 v[68:71], v[164:167], v[220:223], v[68:71]
	v_mfma_f32_16x16x32_bf16 v[64:67], v[172:175], v[220:223], v[64:67]
	v_mfma_f32_16x16x32_bf16 v[116:119], v[168:171], v[200:203], v[116:119]
	v_mfma_f32_16x16x32_bf16 v[112:115], v[192:195], v[200:203], v[112:115]
	v_mfma_f32_16x16x32_bf16 v[100:103], v[168:171], v[208:211], v[100:103]
	v_mfma_f32_16x16x32_bf16 v[96:99], v[192:195], v[208:211], v[96:99]
	v_mfma_f32_16x16x32_bf16 v[84:87], v[168:171], v[216:219], v[84:87]
	v_mfma_f32_16x16x32_bf16 v[80:83], v[192:195], v[216:219], v[80:83]
	v_mfma_f32_16x16x32_bf16 v[68:71], v[168:171], v[224:227], v[68:71]
	v_mfma_f32_16x16x32_bf16 v[64:67], v[192:195], v[224:227], v[64:67]
	s_barrier
; #define PG8_STAGE(bufoff, gbase, voff) do { _Pragma("unroll") for (int _i = 0; _i < 2; ++_i) \
;         __builtin_amdgcn_global_load_lds((const unsigned*)((const char*)(gbase) + (voff)[_i]), (PG8_LAS unsigned*)(lds + (bufoff) + ldsw + _i * 8192), 16, 0, 0); } while (0)
; #define PG8_LDA(dst, b, h) do { _Pragma("unroll") for (int m = 0; m < 4; ++m) _Pragma("unroll") for (int k = 0; k < 2; ++k) dst[m][k] = *(const PG8_LAS bf16x8*)(lds + PG8_SA(b, h) + aoff + m * 2048 + k * 1024); } while (0)
; #define PG8_MMA(ai, bj, At, Bt) do { __builtin_amdgcn_s_setprio(1); _Pragma("unroll") for (int m = 0; m < 4; ++m) _Pragma("unroll") for (int n = 0; n < 2; ++n) _Pragma("unroll") for (int k = 0; k < 2; ++k) \
;         acc[ai][bj][m][n] = __builtin_amdgcn_mfma_f32_16x16x32_bf16(Bt[n][k], At[m][k], acc[ai][bj][m][n], 0, 0, 0); __builtin_amdgcn_s_setprio(0); } while (0)
; #define PG8_WAIT_V(n) asm volatile("s_waitcnt vmcnt(" #n ")" ::: "memory")
; #define PG8_WAIT_L(n) asm volatile("s_waitcnt lgkmcnt(" #n ")" ::: "memory")
; #define PG8_BAR __builtin_amdgcn_s_barrier()
; #define PG8_SCHED __builtin_amdgcn_sched_barrier(0)
; template <class Epi, class Sched, bool ALIGN_EPI = false, bool SP2 = false>
; __device__ __forceinline__ void gemm_phase(PG8_LAS unsigned char* lds, const Gemm g, const Sched& S, const Epi& E) {
;     ...
;         for (int t = 0; t < nt; t += 2) {
;     ...
;             PG8_LDA(At, 1, 1); PG8_STAGE(PG8_SB(1, 0), b3, voffB); PG8_STAGE(PG8_SB(1, 1), b3 + hstep, voffB); PG8_STAGE(PG8_SA(1, 0), a3, voffA);
;             PG8_WAIT_V(8); PG8_WAIT_L(0); PG8_BAR; PG8_MMA(1, 0, At, B0); PG8_MMA(1, 1, At, B1); PG8_BAR; PG8_SCHED;
	s_add_i32 s46, s93, s63
	v_lshl_add_u64 v[146:147], v[146:147], 0, s[18:19]
	s_mov_b32 m0, s46
	ds_read_b128 v[196:199], v151 offset:49152
	ds_read_b128 v[200:203], v151 offset:50176
	ds_read_b128 v[204:207], v151 offset:51200
	ds_read_b128 v[208:211], v151 offset:52224
	ds_read_b128 v[212:215], v151 offset:53248
	ds_read_b128 v[216:219], v151 offset:54272
	ds_read_b128 v[220:223], v151 offset:55296
	ds_read_b128 v[224:227], v151 offset:56320
	global_load_lds_dwordx4 v[146:147], off
	v_lshl_add_u64 v[146:147], v[182:183], 0, s[18:19]
	s_add_i32 m0, s46, 0x2000
	s_add_i32 s46, s68, s63
	global_load_lds_dwordx4 v[146:147], off
	v_lshl_add_u64 v[146:147], v[184:185], 0, s[18:19]
	s_mov_b32 m0, s46
	s_nop 0
	global_load_lds_dwordx4 v[146:147], off
	v_lshl_add_u64 v[146:147], v[188:189], 0, s[18:19]
	s_add_i32 m0, s46, 0x2000
	s_nop 0
	global_load_lds_dwordx4 v[146:147], off
	v_lshl_add_u64 v[146:147], v[190:191], 0, s[18:19]
	s_mov_b32 m0, s0
	s_nop 0
	global_load_lds_dwordx4 v[146:147], off
	v_lshl_add_u64 v[146:147], v[228:229], 0, s[18:19]
	s_mov_b32 m0, s58
	s_nop 0
	global_load_lds_dwordx4 v[146:147], off
	s_waitcnt vmcnt(8)
	s_waitcnt lgkmcnt(0)
	s_barrier
	v_mfma_f32_16x16x32_bf16 v[60:63], v[138:141], v[196:199], v[60:63]
	v_mfma_f32_16x16x32_bf16 v[56:59], v[156:159], v[196:199], v[56:59]
	v_mfma_f32_16x16x32_bf16 v[44:47], v[138:141], v[204:207], v[44:47]
	v_mfma_f32_16x16x32_bf16 v[40:43], v[156:159], v[204:207], v[40:43]
	v_mfma_f32_16x16x32_bf16 v[28:31], v[138:141], v[212:215], v[28:31]
	v_mfma_f32_16x16x32_bf16 v[24:27], v[156:159], v[212:215], v[24:27]
	v_mfma_f32_16x16x32_bf16 v[12:15], v[138:141], v[220:223], v[12:15]
	v_mfma_f32_16x16x32_bf16 v[8:11], v[156:159], v[220:223], v[8:11]
	v_mfma_f32_16x16x32_bf16 v[60:63], v[142:145], v[200:203], v[60:63]
	v_mfma_f32_16x16x32_bf16 v[56:59], v[160:163], v[200:203], v[56:59]
	v_mfma_f32_16x16x32_bf16 v[44:47], v[142:145], v[208:211], v[44:47]
	v_mfma_f32_16x16x32_bf16 v[40:43], v[160:163], v[208:211], v[40:43]
	v_mfma_f32_16x16x32_bf16 v[28:31], v[142:145], v[216:219], v[28:31]
	v_mfma_f32_16x16x32_bf16 v[24:27], v[160:163], v[216:219], v[24:27]
	v_mfma_f32_16x16x32_bf16 v[12:15], v[142:145], v[224:227], v[12:15]
	v_mfma_f32_16x16x32_bf16 v[8:11], v[160:163], v[224:227], v[8:11]
	v_mfma_f32_16x16x32_bf16 v[52:55], v[164:167], v[196:199], v[52:55]
	v_mfma_f32_16x16x32_bf16 v[48:51], v[172:175], v[196:199], v[48:51]
	v_mfma_f32_16x16x32_bf16 v[36:39], v[164:167], v[204:207], v[36:39]
	v_mfma_f32_16x16x32_bf16 v[32:35], v[172:175], v[204:207], v[32:35]
	v_mfma_f32_16x16x32_bf16 v[20:23], v[164:167], v[212:215], v[20:23]
	v_mfma_f32_16x16x32_bf16 v[16:19], v[172:175], v[212:215], v[16:19]
	v_mfma_f32_16x16x32_bf16 v[4:7], v[164:167], v[220:223], v[4:7]
	v_mfma_f32_16x16x32_bf16 v[0:3], v[172:175], v[220:223], v[0:3]
	v_mfma_f32_16x16x32_bf16 v[52:55], v[168:171], v[200:203], v[52:55]
	v_mfma_f32_16x16x32_bf16 v[48:51], v[192:195], v[200:203], v[48:51]
	v_mfma_f32_16x16x32_bf16 v[36:39], v[168:171], v[208:211], v[36:39]
	v_mfma_f32_16x16x32_bf16 v[32:35], v[192:195], v[208:211], v[32:35]
	v_mfma_f32_16x16x32_bf16 v[20:23], v[168:171], v[216:219], v[20:23]
	v_mfma_f32_16x16x32_bf16 v[16:19], v[192:195], v[216:219], v[16:19]
	v_mfma_f32_16x16x32_bf16 v[4:7], v[168:171], v[224:227], v[4:7]
	v_mfma_f32_16x16x32_bf16 v[0:3], v[192:195], v[224:227], v[0:3]
	s_barrier
	s_add_u32 s44, s44, 0x100
	s_addc_u32 s45, s45, 0
	s_add_u32 s86, s86, 0x100
	s_addc_u32 s87, s87, 0
	s_cmp_ge_u32 vcc_lo, s14
	s_mov_b32 s46, vcc_lo
	s_cbranch_scc0 .LBB0_218
	s_and_b64 vcc, exec, s[36:37]
	s_cbranch_vccz .LBB0_221
	s_barrier

; #define PG8_STAGE(bufoff, gbase, voff) do { _Pragma("unroll") for (int _i = 0; _i < 2; ++_i) \
;         __builtin_amdgcn_global_load_lds((const unsigned*)((const char*)(gbase) + (voff)[_i]), (PG8_LAS unsigned*)(lds + (bufoff) + ldsw + _i * 8192), 16, 0, 0); } while (0)
; #define PG8_LDA(dst, b, h) do { _Pragma("unroll") for (int m = 0; m < 4; ++m) _Pragma("unroll") for (int k = 0; k < 2; ++k) dst[m][k] = *(const PG8_LAS bf16x8*)(lds + PG8_SA(b, h) + aoff + m * 2048 + k * 1024); } while (0)
; #define PG8_LDB(dst, b, h) do { _Pragma("unroll") for (int n = 0; n < 2; ++n) _Pragma("unroll") for (int k = 0; k < 2; ++k) dst[n][k] = *(const PG8_LAS bf16x8*)(lds + PG8_SB(b, h) + boff + n * 2048 + k * 1024); } while (0)
; #define PG8_MMA(ai, bj, At, Bt) do { __builtin_amdgcn_s_setprio(1); _Pragma("unroll") for (int m = 0; m < 4; ++m) _Pragma("unroll") for (int n = 0; n < 2; ++n) _Pragma("unroll") for (int k = 0; k < 2; ++k) \
;         acc[ai][bj][m][n] = __builtin_amdgcn_mfma_f32_16x16x32_bf16(Bt[n][k], At[m][k], acc[ai][bj][m][n], 0, 0, 0); __builtin_amdgcn_s_setprio(0); } while (0)
; #define PG8_WAIT_V(n) asm volatile("s_waitcnt vmcnt(" #n ")" ::: "memory")
; #define PG8_WAIT_L(n) asm volatile("s_waitcnt lgkmcnt(" #n ")" ::: "memory")
; #define PG8_BAR __builtin_amdgcn_s_barrier()
; #define PG8_SCHED __builtin_amdgcn_sched_barrier(0)
; template <class Epi, class Sched, bool ALIGN_EPI = false, bool SP2 = false>
; __device__ __forceinline__ void gemm_phase(PG8_LAS unsigned char* lds, const Gemm g, const Sched& S, const Epi& E) {
;     ...
;             PG8_LDB(B0, 0, 0); PG8_LDB(B1, 0, 1); PG8_SCHED; PG8_LDA(At, 0, 0); PG8_STAGE(PG8_SA(1, 1), a1 + hstep, voffA);
;             PG8_WAIT_V(8); PG8_WAIT_L(0); PG8_BAR; PG8_MMA(0, 0, At, B0); PG8_MMA(0, 1, At, B1); PG8_BAR; PG8_SCHED;
;             PG8_LDA(At, 0, 1); PG8_STAGE(PG8_SB(0, 0), b2, voffB); PG8_STAGE(PG8_SB(0, 1), b2 + hstep, voffB); PG8_STAGE(PG8_SA(0, 0), a2, voffA);
.LBB0_331:
	s_add_u32 s68, s74, 0xfff80080
	s_addc_u32 s69, s75, -1
	s_add_i32 s82, 0, 0x10000
	s_cmp_eq_u32 s81, 28
	s_cselect_b32 s79, s45, s69
	s_cselect_b32 s78, s59, s68
	v_add_u32_e32 v140, s82, v143
	s_cselect_b32 s77, s43, s80
	s_cselect_b32 s76, s63, s71
	s_add_i32 s68, 0, 0x14000
	ds_read_b128 v[146:149], v140
	ds_read_b128 v[156:159], v140 offset:1024
	ds_read_b128 v[160:163], v140 offset:2048
	ds_read_b128 v[164:167], v140 offset:3072
	v_add_u32_e32 v140, s68, v143
	ds_read_b128 v[168:171], v140
	ds_read_b128 v[172:175], v140 offset:1024
	ds_read_b128 v[192:195], v140 offset:2048
	ds_read_b128 v[196:199], v140 offset:3072
	v_lshl_add_u64 v[140:141], s[74:75], 0, v[136:137]
	s_add_i32 m0, s16, 0xc000
	ds_read_b128 v[200:203], v145
	ds_read_b128 v[204:207], v145 offset:1024
	ds_read_b128 v[208:211], v145 offset:2048
	ds_read_b128 v[212:215], v145 offset:3072
	ds_read_b128 v[216:219], v145 offset:4096
	ds_read_b128 v[220:223], v145 offset:5120
	ds_read_b128 v[224:227], v145 offset:6144
	ds_read_b128 v[228:231], v145 offset:7168
	global_load_lds_dwordx4 v[140:141], off
	v_lshl_add_u64 v[140:141], s[74:75], 0, v[138:139]
	s_add_i32 m0, s16, 0xe000
	s_nop 0
	global_load_lds_dwordx4 v[140:141], off
	s_waitcnt vmcnt(8)
	s_waitcnt lgkmcnt(0)
	s_barrier
	v_mfma_f32_16x16x32_bf16 v[116:119], v[146:149], v[200:203], v[116:119]
	v_mfma_f32_16x16x32_bf16 v[112:115], v[160:163], v[200:203], v[112:115]
	v_mfma_f32_16x16x32_bf16 v[104:107], v[146:149], v[208:211], v[104:107]
	v_mfma_f32_16x16x32_bf16 v[96:99], v[160:163], v[208:211], v[96:99]
	v_mfma_f32_16x16x32_bf16 v[88:91], v[146:149], v[216:219], v[88:91]
	v_mfma_f32_16x16x32_bf16 v[80:83], v[160:163], v[216:219], v[80:83]
	v_mfma_f32_16x16x32_bf16 v[72:75], v[146:149], v[224:227], v[72:75]
	v_mfma_f32_16x16x32_bf16 v[64:67], v[160:163], v[224:227], v[64:67]
	v_mfma_f32_16x16x32_bf16 v[116:119], v[156:159], v[204:207], v[116:119]
	v_mfma_f32_16x16x32_bf16 v[112:115], v[164:167], v[204:207], v[112:115]
	v_mfma_f32_16x16x32_bf16 v[104:107], v[156:159], v[212:215], v[104:107]
	v_mfma_f32_16x16x32_bf16 v[96:99], v[164:167], v[212:215], v[96:99]
	v_mfma_f32_16x16x32_bf16 v[88:91], v[156:159], v[220:223], v[88:91]
	v_mfma_f32_16x16x32_bf16 v[80:83], v[164:167], v[220:223], v[80:83]
	v_mfma_f32_16x16x32_bf16 v[72:75], v[156:159], v[228:231], v[72:75]
	v_mfma_f32_16x16x32_bf16 v[64:67], v[164:167], v[228:231], v[64:67]
	v_mfma_f32_16x16x32_bf16 v[124:127], v[168:171], v[200:203], v[124:127]
	v_mfma_f32_16x16x32_bf16 v[120:123], v[192:195], v[200:203], v[120:123]
	v_mfma_f32_16x16x32_bf16 v[108:111], v[168:171], v[208:211], v[108:111]
	v_mfma_f32_16x16x32_bf16 v[100:103], v[192:195], v[208:211], v[100:103]
	v_mfma_f32_16x16x32_bf16 v[92:95], v[168:171], v[216:219], v[92:95]
	v_mfma_f32_16x16x32_bf16 v[84:87], v[192:195], v[216:219], v[84:87]
	v_mfma_f32_16x16x32_bf16 v[76:79], v[168:171], v[224:227], v[76:79]
	v_mfma_f32_16x16x32_bf16 v[68:71], v[192:195], v[224:227], v[68:71]
	v_mfma_f32_16x16x32_bf16 v[124:127], v[172:175], v[204:207], v[124:127]
	v_mfma_f32_16x16x32_bf16 v[120:123], v[196:199], v[204:207], v[120:123]
	v_mfma_f32_16x16x32_bf16 v[108:111], v[172:175], v[212:215], v[108:111]
	v_mfma_f32_16x16x32_bf16 v[100:103], v[196:199], v[212:215], v[100:103]
	v_mfma_f32_16x16x32_bf16 v[92:95], v[172:175], v[220:223], v[92:95]
	v_mfma_f32_16x16x32_bf16 v[84:87], v[196:199], v[220:223], v[84:87]
	v_mfma_f32_16x16x32_bf16 v[76:79], v[172:175], v[228:231], v[76:79]
	v_mfma_f32_16x16x32_bf16 v[68:71], v[196:199], v[228:231], v[68:71]
	s_barrier
	s_add_i32 s69, s82, s15
	v_lshl_add_u64 v[140:141], s[76:77], 0, v[152:153]
	s_mov_b32 m0, s69
	ds_read_b128 v[200:203], v145 offset:16384
	ds_read_b128 v[204:207], v145 offset:17408
	ds_read_b128 v[208:211], v145 offset:18432
	ds_read_b128 v[212:215], v145 offset:19456
	ds_read_b128 v[216:219], v145 offset:20480
	ds_read_b128 v[220:223], v145 offset:21504
	ds_read_b128 v[224:227], v145 offset:22528
	ds_read_b128 v[228:231], v145 offset:23552
	global_load_lds_dwordx4 v[140:141], off
	s_add_i32 m0, s69, 0x2000
	s_add_u32 s82, s76, 0x80000
	v_lshl_add_u64 v[150:151], s[76:77], 0, v[128:129]
	s_addc_u32 s83, s77, 0
	s_add_i32 s68, s68, s15
	global_load_lds_dwordx4 v[150:151], off
	v_lshl_add_u64 v[182:183], s[82:83], 0, v[152:153]
	s_mov_b32 m0, s68
	v_lshl_add_u64 v[184:185], s[78:79], 0, v[130:131]
	global_load_lds_dwordx4 v[182:183], off
	v_lshl_add_u64 v[182:183], s[82:83], 0, v[128:129]
	s_add_i32 m0, s68, 0x2000
	s_nop 0
	global_load_lds_dwordx4 v[182:183], off
	v_lshl_add_u64 v[182:183], s[78:79], 0, v[132:133]
	s_mov_b32 m0, s16
	s_nop 0
	global_load_lds_dwordx4 v[182:183], off
	s_mov_b32 m0, s17
	s_nop 0
	global_load_lds_dwordx4 v[184:185], off
	s_waitcnt vmcnt(8)
	s_waitcnt lgkmcnt(0)
	s_barrier
; #define PG8_STAGE(bufoff, gbase, voff) do { _Pragma("unroll") for (int _i = 0; _i < 2; ++_i) \
;         __builtin_amdgcn_global_load_lds((const unsigned*)((const char*)(gbase) + (voff)[_i]), (PG8_LAS unsigned*)(lds + (bufoff) + ldsw + _i * 8192), 16, 0, 0); } while (0)
; #define PG8_LDA(dst, b, h) do { _Pragma("unroll") for (int m = 0; m < 4; ++m) _Pragma("unroll") for (int k = 0; k < 2; ++k) dst[m][k] = *(const PG8_LAS bf16x8*)(lds + PG8_SA(b, h) + aoff + m * 2048 + k * 1024); } while (0)
; #define PG8_LDB(dst, b, h) do { _Pragma("unroll") for (int n = 0; n < 2; ++n) _Pragma("unroll") for (int k = 0; k < 2; ++k) dst[n][k] = *(const PG8_LAS bf16x8*)(lds + PG8_SB(b, h) + boff + n * 2048 + k * 1024); } while (0)
; #define PG8_MMA(ai, bj, At, Bt) do { __builtin_amdgcn_s_setprio(1); _Pragma("unroll") for (int m = 0; m < 4; ++m) _Pragma("unroll") for (int n = 0; n < 2; ++n) _Pragma("unroll") for (int k = 0; k < 2; ++k) \
;         acc[ai][bj][m][n] = __builtin_amdgcn_mfma_f32_16x16x32_bf16(Bt[n][k], At[m][k], acc[ai][bj][m][n], 0, 0, 0); __builtin_amdgcn_s_setprio(0); } while (0)
; #define PG8_WAIT_V(n) asm volatile("s_waitcnt vmcnt(" #n ")" ::: "memory")
; #define PG8_WAIT_L(n) asm volatile("s_waitcnt lgkmcnt(" #n ")" ::: "memory")
; #define PG8_BAR __builtin_amdgcn_s_barrier()
; #define PG8_SCHED __builtin_amdgcn_sched_barrier(0)
; template <class Epi, class Sched, bool ALIGN_EPI = false, bool SP2 = false>
; __device__ __forceinline__ void gemm_phase(PG8_LAS unsigned char* lds, const Gemm g, const Sched& S, const Epi& E) {
;     ...
;             PG8_WAIT_V(8); PG8_WAIT_L(0); PG8_BAR; PG8_MMA(1, 0, At, B0); PG8_MMA(1, 1, At, B1); PG8_BAR; PG8_SCHED;
;             PG8_LDB(B0, 1, 0); PG8_LDB(B1, 1, 1); PG8_SCHED; PG8_LDA(At, 1, 0); PG8_STAGE(PG8_SA(0, 1), a2 + hstep, voffA);
;             PG8_WAIT_V(8); PG8_WAIT_L(0); PG8_BAR; PG8_MMA(0, 0, At, B0); PG8_MMA(0, 1, At, B1); PG8_BAR; PG8_SCHED;
;             PG8_LDA(At, 1, 1); PG8_STAGE(PG8_SB(1, 0), b3, voffB); PG8_STAGE(PG8_SB(1, 1), b3 + hstep, voffB); PG8_STAGE(PG8_SA(1, 0), a3, voffA);
	v_mfma_f32_16x16x32_bf16 v[56:59], v[146:149], v[200:203], v[56:59]
	v_mfma_f32_16x16x32_bf16 v[48:51], v[160:163], v[200:203], v[48:51]
	v_mfma_f32_16x16x32_bf16 v[40:43], v[146:149], v[208:211], v[40:43]
	v_mfma_f32_16x16x32_bf16 v[32:35], v[160:163], v[208:211], v[32:35]
	v_mfma_f32_16x16x32_bf16 v[24:27], v[146:149], v[216:219], v[24:27]
	v_mfma_f32_16x16x32_bf16 v[16:19], v[160:163], v[216:219], v[16:19]
	v_mfma_f32_16x16x32_bf16 v[8:11], v[146:149], v[224:227], v[8:11]
	v_mfma_f32_16x16x32_bf16 v[4:7], v[160:163], v[224:227], v[4:7]
	v_mfma_f32_16x16x32_bf16 v[56:59], v[156:159], v[204:207], v[56:59]
	v_mfma_f32_16x16x32_bf16 v[48:51], v[164:167], v[204:207], v[48:51]
	v_mfma_f32_16x16x32_bf16 v[40:43], v[156:159], v[212:215], v[40:43]
	v_mfma_f32_16x16x32_bf16 v[32:35], v[164:167], v[212:215], v[32:35]
	v_mfma_f32_16x16x32_bf16 v[24:27], v[156:159], v[220:223], v[24:27]
	v_mfma_f32_16x16x32_bf16 v[16:19], v[164:167], v[220:223], v[16:19]
	v_mfma_f32_16x16x32_bf16 v[8:11], v[156:159], v[228:231], v[8:11]
	v_mfma_f32_16x16x32_bf16 v[4:7], v[164:167], v[228:231], v[4:7]
	v_mfma_f32_16x16x32_bf16 v[60:63], v[168:171], v[200:203], v[60:63]
	v_mfma_f32_16x16x32_bf16 v[52:55], v[192:195], v[200:203], v[52:55]
	v_mfma_f32_16x16x32_bf16 v[44:47], v[168:171], v[208:211], v[44:47]
	v_mfma_f32_16x16x32_bf16 v[36:39], v[192:195], v[208:211], v[36:39]
	v_mfma_f32_16x16x32_bf16 v[28:31], v[168:171], v[216:219], v[28:31]
	v_mfma_f32_16x16x32_bf16 v[20:23], v[192:195], v[216:219], v[20:23]
	v_mfma_f32_16x16x32_bf16 v[12:15], v[168:171], v[224:227], v[12:15]
	v_mfma_f32_16x16x32_bf16 v[0:3], v[192:195], v[224:227], v[0:3]
	v_mfma_f32_16x16x32_bf16 v[60:63], v[172:175], v[204:207], v[60:63]
	v_mfma_f32_16x16x32_bf16 v[52:55], v[196:199], v[204:207], v[52:55]
	v_mfma_f32_16x16x32_bf16 v[44:47], v[172:175], v[212:215], v[44:47]
	v_mfma_f32_16x16x32_bf16 v[36:39], v[196:199], v[212:215], v[36:39]
	v_mfma_f32_16x16x32_bf16 v[28:31], v[172:175], v[220:223], v[28:31]
	v_mfma_f32_16x16x32_bf16 v[20:23], v[196:199], v[220:223], v[20:23]
	v_mfma_f32_16x16x32_bf16 v[12:15], v[172:175], v[228:231], v[12:15]
	v_mfma_f32_16x16x32_bf16 v[0:3], v[196:199], v[228:231], v[0:3]
	s_barrier
	v_add_u32_e32 v155, s93, v143
	s_add_i32 s68, 0, 0x1c000
	ds_read_b128 v[146:149], v155
	ds_read_b128 v[156:159], v155 offset:1024
	ds_read_b128 v[160:163], v155 offset:2048
	ds_read_b128 v[164:167], v155 offset:3072
	v_add_u32_e32 v155, s68, v143
	ds_read_b128 v[168:171], v155
	ds_read_b128 v[172:175], v155 offset:1024
	ds_read_b128 v[192:195], v155 offset:2048
	ds_read_b128 v[196:199], v155 offset:3072
	s_add_u32 s78, s78, 0x80000
	s_addc_u32 s79, s79, 0
	s_mov_b32 m0, s22
	v_lshl_add_u64 v[188:189], s[78:79], 0, v[132:133]
	ds_read_b128 v[200:203], v145 offset:32768
	ds_read_b128 v[204:207], v145 offset:33792
	ds_read_b128 v[208:211], v145 offset:34816
	ds_read_b128 v[212:215], v145 offset:35840
	ds_read_b128 v[216:219], v145 offset:36864
	ds_read_b128 v[220:223], v145 offset:37888
	ds_read_b128 v[224:227], v145 offset:38912
	ds_read_b128 v[228:231], v145 offset:39936
	global_load_lds_dwordx4 v[188:189], off
	v_lshl_add_u64 v[188:189], s[78:79], 0, v[130:131]
	s_mov_b32 m0, s23
	s_nop 0
	global_load_lds_dwordx4 v[188:189], off
	s_waitcnt vmcnt(8)
	s_waitcnt lgkmcnt(0)
	s_barrier
	v_mfma_f32_16x16x32_bf16 v[116:119], v[146:149], v[200:203], v[116:119]
	v_mfma_f32_16x16x32_bf16 v[112:115], v[160:163], v[200:203], v[112:115]
	v_mfma_f32_16x16x32_bf16 v[104:107], v[146:149], v[208:211], v[104:107]
	v_mfma_f32_16x16x32_bf16 v[96:99], v[160:163], v[208:211], v[96:99]
	v_mfma_f32_16x16x32_bf16 v[88:91], v[146:149], v[216:219], v[88:91]
	v_mfma_f32_16x16x32_bf16 v[80:83], v[160:163], v[216:219], v[80:83]
	v_mfma_f32_16x16x32_bf16 v[72:75], v[146:149], v[224:227], v[72:75]
	v_mfma_f32_16x16x32_bf16 v[64:67], v[160:163], v[224:227], v[64:67]
	v_mfma_f32_16x16x32_bf16 v[116:119], v[156:159], v[204:207], v[116:119]
	v_mfma_f32_16x16x32_bf16 v[112:115], v[164:167], v[204:207], v[112:115]
	v_mfma_f32_16x16x32_bf16 v[104:107], v[156:159], v[212:215], v[104:107]
	v_mfma_f32_16x16x32_bf16 v[96:99], v[164:167], v[212:215], v[96:99]
	v_mfma_f32_16x16x32_bf16 v[88:91], v[156:159], v[220:223], v[88:91]
	v_mfma_f32_16x16x32_bf16 v[80:83], v[164:167], v[220:223], v[80:83]
	v_mfma_f32_16x16x32_bf16 v[72:75], v[156:159], v[228:231], v[72:75]
	v_mfma_f32_16x16x32_bf16 v[64:67], v[164:167], v[228:231], v[64:67]
	v_mfma_f32_16x16x32_bf16 v[124:127], v[168:171], v[200:203], v[124:127]
	v_mfma_f32_16x16x32_bf16 v[120:123], v[192:195], v[200:203], v[120:123]
	v_mfma_f32_16x16x32_bf16 v[108:111], v[168:171], v[208:211], v[108:111]
	v_mfma_f32_16x16x32_bf16 v[100:103], v[192:195], v[208:211], v[100:103]
	v_mfma_f32_16x16x32_bf16 v[92:95], v[168:171], v[216:219], v[92:95]
	v_mfma_f32_16x16x32_bf16 v[84:87], v[192:195], v[216:219], v[84:87]
	v_mfma_f32_16x16x32_bf16 v[76:79], v[168:171], v[224:227], v[76:79]
	v_mfma_f32_16x16x32_bf16 v[68:71], v[192:195], v[224:227], v[68:71]
	v_mfma_f32_16x16x32_bf16 v[124:127], v[172:175], v[204:207], v[124:127]
	v_mfma_f32_16x16x32_bf16 v[120:123], v[196:199], v[204:207], v[120:123]
	v_mfma_f32_16x16x32_bf16 v[108:111], v[172:175], v[212:215], v[108:111]
	v_mfma_f32_16x16x32_bf16 v[100:103], v[196:199], v[212:215], v[100:103]
	v_mfma_f32_16x16x32_bf16 v[92:95], v[172:175], v[220:223], v[92:95]
	v_mfma_f32_16x16x32_bf16 v[84:87], v[196:199], v[220:223], v[84:87]
	v_mfma_f32_16x16x32_bf16 v[76:79], v[172:175], v[228:231], v[76:79]
	v_mfma_f32_16x16x32_bf16 v[68:71], v[196:199], v[228:231], v[68:71]
	s_barrier
; #define PG8_STAGE(bufoff, gbase, voff) do { _Pragma("unroll") for (int _i = 0; _i < 2; ++_i) \
;         __builtin_amdgcn_global_load_lds((const unsigned*)((const char*)(gbase) + (voff)[_i]), (PG8_LAS unsigned*)(lds + (bufoff) + ldsw + _i * 8192), 16, 0, 0); } while (0)
; #define PG8_LDA(dst, b, h) do { _Pragma("unroll") for (int m = 0; m < 4; ++m) _Pragma("unroll") for (int k = 0; k < 2; ++k) dst[m][k] = *(const PG8_LAS bf16x8*)(lds + PG8_SA(b, h) + aoff + m * 2048 + k * 1024); } while (0)
; #define PG8_MMA(ai, bj, At, Bt) do { __builtin_amdgcn_s_setprio(1); _Pragma("unroll") for (int m = 0; m < 4; ++m) _Pragma("unroll") for (int n = 0; n < 2; ++n) _Pragma("unroll") for (int k = 0; k < 2; ++k) \
;         acc[ai][bj][m][n] = __builtin_amdgcn_mfma_f32_16x16x32_bf16(Bt[n][k], At[m][k], acc[ai][bj][m][n], 0, 0, 0); __builtin_amdgcn_s_setprio(0); } while (0)
; #define PG8_WAIT_V(n) asm volatile("s_waitcnt vmcnt(" #n ")" ::: "memory")
; #define PG8_WAIT_L(n) asm volatile("s_waitcnt lgkmcnt(" #n ")" ::: "memory")
; #define PG8_BAR __builtin_amdgcn_s_barrier()
; #define PG8_SCHED __builtin_amdgcn_sched_barrier(0)
; template <class Epi, class Sched, bool ALIGN_EPI = false, bool SP2 = false>
; __device__ __forceinline__ void gemm_phase(PG8_LAS unsigned char* lds, const Gemm g, const Sched& S, const Epi& E) {
;     ...
;         for (int t = 0; t < nt; t += 2) {
;     ...
;             PG8_LDA(At, 1, 1); PG8_STAGE(PG8_SB(1, 0), b3, voffB); PG8_STAGE(PG8_SB(1, 1), b3 + hstep, voffB); PG8_STAGE(PG8_SA(1, 0), a3, voffA);
;             PG8_WAIT_V(8); PG8_WAIT_L(0); PG8_BAR; PG8_MMA(1, 0, At, B0); PG8_MMA(1, 1, At, B1); PG8_BAR; PG8_SCHED;
	s_add_i32 s69, s93, s15
	v_lshl_add_u64 v[140:141], v[140:141], 0, s[18:19]
	s_mov_b32 m0, s69
	ds_read_b128 v[200:203], v145 offset:49152
	ds_read_b128 v[204:207], v145 offset:50176
	ds_read_b128 v[208:211], v145 offset:51200
	ds_read_b128 v[212:215], v145 offset:52224
	ds_read_b128 v[216:219], v145 offset:53248
	ds_read_b128 v[220:223], v145 offset:54272
	ds_read_b128 v[224:227], v145 offset:55296
	ds_read_b128 v[228:231], v145 offset:56320
	global_load_lds_dwordx4 v[140:141], off
	s_add_i32 m0, s69, 0x2000
	s_add_u32 s76, s76, 0x80080
	v_lshl_add_u64 v[140:141], v[150:151], 0, s[18:19]
	s_addc_u32 s77, s77, 0
	s_add_i32 s68, s68, s15
	global_load_lds_dwordx4 v[140:141], off
	v_lshl_add_u64 v[140:141], s[76:77], 0, v[152:153]
	s_mov_b32 m0, s68
	s_nop 0
	global_load_lds_dwordx4 v[140:141], off
	v_lshl_add_u64 v[140:141], s[76:77], 0, v[128:129]
	s_add_i32 m0, s68, 0x2000
	s_nop 0
	global_load_lds_dwordx4 v[140:141], off
	v_lshl_add_u64 v[140:141], v[182:183], 0, s[18:19]
	s_mov_b32 m0, s26
	s_nop 0
	global_load_lds_dwordx4 v[140:141], off
	v_lshl_add_u64 v[140:141], v[184:185], 0, s[18:19]
	s_mov_b32 m0, s34
	s_nop 0
	global_load_lds_dwordx4 v[140:141], off
	s_waitcnt vmcnt(8)
	s_waitcnt lgkmcnt(0)
	s_barrier
	v_mfma_f32_16x16x32_bf16 v[56:59], v[146:149], v[200:203], v[56:59]
	v_mfma_f32_16x16x32_bf16 v[48:51], v[160:163], v[200:203], v[48:51]
	v_mfma_f32_16x16x32_bf16 v[40:43], v[146:149], v[208:211], v[40:43]
	v_mfma_f32_16x16x32_bf16 v[32:35], v[160:163], v[208:211], v[32:35]
	v_mfma_f32_16x16x32_bf16 v[24:27], v[146:149], v[216:219], v[24:27]
	v_mfma_f32_16x16x32_bf16 v[16:19], v[160:163], v[216:219], v[16:19]
	v_mfma_f32_16x16x32_bf16 v[8:11], v[146:149], v[224:227], v[8:11]
	v_mfma_f32_16x16x32_bf16 v[4:7], v[160:163], v[224:227], v[4:7]
	v_mfma_f32_16x16x32_bf16 v[56:59], v[156:159], v[204:207], v[56:59]
	v_mfma_f32_16x16x32_bf16 v[48:51], v[164:167], v[204:207], v[48:51]
	v_mfma_f32_16x16x32_bf16 v[40:43], v[156:159], v[212:215], v[40:43]
	v_mfma_f32_16x16x32_bf16 v[32:35], v[164:167], v[212:215], v[32:35]
	v_mfma_f32_16x16x32_bf16 v[24:27], v[156:159], v[220:223], v[24:27]
	v_mfma_f32_16x16x32_bf16 v[16:19], v[164:167], v[220:223], v[16:19]
	v_mfma_f32_16x16x32_bf16 v[8:11], v[156:159], v[228:231], v[8:11]
	v_mfma_f32_16x16x32_bf16 v[4:7], v[164:167], v[228:231], v[4:7]
	v_mfma_f32_16x16x32_bf16 v[60:63], v[168:171], v[200:203], v[60:63]
	v_mfma_f32_16x16x32_bf16 v[52:55], v[192:195], v[200:203], v[52:55]
	v_mfma_f32_16x16x32_bf16 v[44:47], v[168:171], v[208:211], v[44:47]
	v_mfma_f32_16x16x32_bf16 v[36:39], v[192:195], v[208:211], v[36:39]
	v_mfma_f32_16x16x32_bf16 v[28:31], v[168:171], v[216:219], v[28:31]
	v_mfma_f32_16x16x32_bf16 v[20:23], v[192:195], v[216:219], v[20:23]
	v_mfma_f32_16x16x32_bf16 v[12:15], v[168:171], v[224:227], v[12:15]
	v_mfma_f32_16x16x32_bf16 v[0:3], v[192:195], v[224:227], v[0:3]
	v_mfma_f32_16x16x32_bf16 v[60:63], v[172:175], v[204:207], v[60:63]
	v_mfma_f32_16x16x32_bf16 v[52:55], v[196:199], v[204:207], v[52:55]
	v_mfma_f32_16x16x32_bf16 v[44:47], v[172:175], v[212:215], v[44:47]
	v_mfma_f32_16x16x32_bf16 v[36:39], v[196:199], v[212:215], v[36:39]
	v_mfma_f32_16x16x32_bf16 v[28:31], v[172:175], v[220:223], v[28:31]
	v_mfma_f32_16x16x32_bf16 v[20:23], v[196:199], v[220:223], v[20:23]
	v_mfma_f32_16x16x32_bf16 v[12:15], v[172:175], v[228:231], v[12:15]
	v_mfma_f32_16x16x32_bf16 v[0:3], v[196:199], v[228:231], v[0:3]
	s_barrier
	s_add_i32 s81, s81, 2
	s_add_u32 s74, s74, 0x100
	s_addc_u32 s75, s75, 0
	s_add_u32 s71, s71, 0x100
	s_addc_u32 s80, s80, 0
	s_cmp_gt_u32 s81, 29
	s_cbranch_scc0 .LBB0_331
	s_and_b64 vcc, exec, s[36:37]
	s_cbranch_vccz .LBB0_334
	s_barrier

; #define PG8_STAGE(bufoff, gbase, voff) do { _Pragma("unroll") for (int _i = 0; _i < 2; ++_i) \
;         __builtin_amdgcn_global_load_lds((const unsigned*)((const char*)(gbase) + (voff)[_i]), (PG8_LAS unsigned*)(lds + (bufoff) + ldsw + _i * 8192), 16, 0, 0); } while (0)
; #define PG8_LDA(dst, b, h) do { _Pragma("unroll") for (int m = 0; m < 4; ++m) _Pragma("unroll") for (int k = 0; k < 2; ++k) dst[m][k] = *(const PG8_LAS bf16x8*)(lds + PG8_SA(b, h) + aoff + m * 2048 + k * 1024); } while (0)
; #define PG8_LDB(dst, b, h) do { _Pragma("unroll") for (int n = 0; n < 2; ++n) _Pragma("unroll") for (int k = 0; k < 2; ++k) dst[n][k] = *(const PG8_LAS bf16x8*)(lds + PG8_SB(b, h) + boff + n * 2048 + k * 1024); } while (0)
; #define PG8_MMA(ai, bj, At, Bt) do { __builtin_amdgcn_s_setprio(1); _Pragma("unroll") for (int m = 0; m < 4; ++m) _Pragma("unroll") for (int n = 0; n < 2; ++n) _Pragma("unroll") for (int k = 0; k < 2; ++k) \
;         acc[ai][bj][m][n] = __builtin_amdgcn_mfma_f32_16x16x32_bf16(Bt[n][k], At[m][k], acc[ai][bj][m][n], 0, 0, 0); __builtin_amdgcn_s_setprio(0); } while (0)
; #define PG8_WAIT_V(n) asm volatile("s_waitcnt vmcnt(" #n ")" ::: "memory")
; #define PG8_WAIT_L(n) asm volatile("s_waitcnt lgkmcnt(" #n ")" ::: "memory")
; #define PG8_BAR __builtin_amdgcn_s_barrier()
; #define PG8_SCHED __builtin_amdgcn_sched_barrier(0)
; template <class Epi, class Sched, bool ALIGN_EPI = false, bool SP2 = false>
; __device__ __forceinline__ void gemm_phase(PG8_LAS unsigned char* lds, const Gemm g, const Sched& S, const Epi& E) {
;     ...
;             PG8_LDB(B0, 0, 0); PG8_LDB(B1, 0, 1); PG8_SCHED; PG8_LDA(At, 0, 0); PG8_STAGE(PG8_SA(1, 1), a1 + hstep, voffA);
;             PG8_WAIT_V(8); PG8_WAIT_L(0); PG8_BAR; PG8_MMA(0, 0, At, B0); PG8_MMA(0, 1, At, B1); PG8_BAR; PG8_SCHED;
;             PG8_LDA(At, 0, 1); PG8_STAGE(PG8_SB(0, 0), b2, voffB); PG8_STAGE(PG8_SB(0, 1), b2 + hstep, voffB); PG8_STAGE(PG8_SA(0, 0), a2, voffA);
.LBB0_354:
	s_add_u32 s68, s48, 0xfff80080
	s_addc_u32 s69, s49, -1
	s_add_i32 s78, 0, 0x10000
	s_cmp_eq_u32 s71, 28
	s_cselect_b32 s77, s41, s69
	s_cselect_b32 s76, s55, s68
	v_add_u32_e32 v150, s78, v139
	s_cselect_b32 s75, s39, s63
	s_cselect_b32 s74, s58, s59
	s_add_i32 s68, 0, 0x14000
	ds_read_b128 v[142:145], v150
	ds_read_b128 v[146:149], v150 offset:1024
	ds_read_b128 v[156:159], v150 offset:2048
	ds_read_b128 v[160:163], v150 offset:3072
	v_add_u32_e32 v150, s68, v139
	ds_read_b128 v[164:167], v150
	ds_read_b128 v[168:171], v150 offset:1024
	ds_read_b128 v[172:175], v150 offset:2048
	ds_read_b128 v[192:195], v150 offset:3072
	v_lshl_add_u64 v[150:151], s[48:49], 0, v[134:135]
	s_add_i32 m0, s16, 0xc000
	ds_read_b128 v[196:199], v141
	ds_read_b128 v[200:203], v141 offset:1024
	ds_read_b128 v[204:207], v141 offset:2048
	ds_read_b128 v[208:211], v141 offset:3072
	ds_read_b128 v[212:215], v141 offset:4096
	ds_read_b128 v[216:219], v141 offset:5120
	ds_read_b128 v[220:223], v141 offset:6144
	ds_read_b128 v[224:227], v141 offset:7168
	global_load_lds_dwordx4 v[150:151], off
	v_lshl_add_u64 v[150:151], s[48:49], 0, v[136:137]
	s_add_i32 m0, s16, 0xe000
	s_nop 0
	global_load_lds_dwordx4 v[150:151], off
	s_waitcnt vmcnt(8)
	s_waitcnt lgkmcnt(0)
	s_barrier
	v_mfma_f32_16x16x32_bf16 v[124:127], v[142:145], v[196:199], v[124:127]
	v_mfma_f32_16x16x32_bf16 v[120:123], v[156:159], v[196:199], v[120:123]
	v_mfma_f32_16x16x32_bf16 v[116:119], v[142:145], v[204:207], v[116:119]
	v_mfma_f32_16x16x32_bf16 v[108:111], v[156:159], v[204:207], v[108:111]
	v_mfma_f32_16x16x32_bf16 v[100:103], v[142:145], v[212:215], v[100:103]
	v_mfma_f32_16x16x32_bf16 v[92:95], v[156:159], v[212:215], v[92:95]
	v_mfma_f32_16x16x32_bf16 v[84:87], v[142:145], v[220:223], v[84:87]
	v_mfma_f32_16x16x32_bf16 v[76:79], v[156:159], v[220:223], v[76:79]
	v_mfma_f32_16x16x32_bf16 v[124:127], v[146:149], v[200:203], v[124:127]
	v_mfma_f32_16x16x32_bf16 v[120:123], v[160:163], v[200:203], v[120:123]
	v_mfma_f32_16x16x32_bf16 v[116:119], v[146:149], v[208:211], v[116:119]
	v_mfma_f32_16x16x32_bf16 v[108:111], v[160:163], v[208:211], v[108:111]
	v_mfma_f32_16x16x32_bf16 v[100:103], v[146:149], v[216:219], v[100:103]
	v_mfma_f32_16x16x32_bf16 v[92:95], v[160:163], v[216:219], v[92:95]
	v_mfma_f32_16x16x32_bf16 v[84:87], v[146:149], v[224:227], v[84:87]
	v_mfma_f32_16x16x32_bf16 v[76:79], v[160:163], v[224:227], v[76:79]
	v_mfma_f32_16x16x32_bf16 v[112:115], v[164:167], v[196:199], v[112:115]
	v_mfma_f32_16x16x32_bf16 v[104:107], v[172:175], v[196:199], v[104:107]
	v_mfma_f32_16x16x32_bf16 v[96:99], v[164:167], v[204:207], v[96:99]
	v_mfma_f32_16x16x32_bf16 v[88:91], v[172:175], v[204:207], v[88:91]
	v_mfma_f32_16x16x32_bf16 v[80:83], v[164:167], v[212:215], v[80:83]
	v_mfma_f32_16x16x32_bf16 v[72:75], v[172:175], v[212:215], v[72:75]
	v_mfma_f32_16x16x32_bf16 v[68:71], v[164:167], v[220:223], v[68:71]
	v_mfma_f32_16x16x32_bf16 v[64:67], v[172:175], v[220:223], v[64:67]
	v_mfma_f32_16x16x32_bf16 v[112:115], v[168:171], v[200:203], v[112:115]
	v_mfma_f32_16x16x32_bf16 v[104:107], v[192:195], v[200:203], v[104:107]
	v_mfma_f32_16x16x32_bf16 v[96:99], v[168:171], v[208:211], v[96:99]
	v_mfma_f32_16x16x32_bf16 v[88:91], v[192:195], v[208:211], v[88:91]
	v_mfma_f32_16x16x32_bf16 v[80:83], v[168:171], v[216:219], v[80:83]
	v_mfma_f32_16x16x32_bf16 v[72:75], v[192:195], v[216:219], v[72:75]
	v_mfma_f32_16x16x32_bf16 v[68:71], v[168:171], v[224:227], v[68:71]
	v_mfma_f32_16x16x32_bf16 v[64:67], v[192:195], v[224:227], v[64:67]
	s_barrier
	s_add_i32 s69, s78, s0
	v_lshl_add_u64 v[150:151], s[74:75], 0, v[152:153]
	s_mov_b32 m0, s69
	ds_read_b128 v[196:199], v141 offset:16384
	ds_read_b128 v[200:203], v141 offset:17408
	ds_read_b128 v[204:207], v141 offset:18432
	ds_read_b128 v[208:211], v141 offset:19456
	ds_read_b128 v[212:215], v141 offset:20480
	ds_read_b128 v[216:219], v141 offset:21504
	ds_read_b128 v[220:223], v141 offset:22528
	ds_read_b128 v[224:227], v141 offset:23552
	global_load_lds_dwordx4 v[150:151], off
	s_add_i32 m0, s69, 0x2000
	s_add_u32 s78, s74, 0x80000
	v_lshl_add_u64 v[182:183], s[74:75], 0, v[132:133]
	s_addc_u32 s79, s75, 0
	s_add_i32 s68, s68, s0
	global_load_lds_dwordx4 v[182:183], off
	v_lshl_add_u64 v[184:185], s[78:79], 0, v[152:153]
	s_mov_b32 m0, s68
	v_lshl_add_u64 v[188:189], s[76:77], 0, v[130:131]
	global_load_lds_dwordx4 v[184:185], off
	v_lshl_add_u64 v[184:185], s[78:79], 0, v[132:133]
	s_add_i32 m0, s68, 0x2000
	s_nop 0
	global_load_lds_dwordx4 v[184:185], off
	v_lshl_add_u64 v[184:185], s[76:77], 0, v[128:129]
	s_mov_b32 m0, s16
	s_nop 0
	global_load_lds_dwordx4 v[184:185], off
	s_mov_b32 m0, s17
	s_nop 0
	global_load_lds_dwordx4 v[188:189], off
	s_waitcnt vmcnt(8)
	s_waitcnt lgkmcnt(0)
	s_barrier
; #define PG8_STAGE(bufoff, gbase, voff) do { _Pragma("unroll") for (int _i = 0; _i < 2; ++_i) \
;         __builtin_amdgcn_global_load_lds((const unsigned*)((const char*)(gbase) + (voff)[_i]), (PG8_LAS unsigned*)(lds + (bufoff) + ldsw + _i * 8192), 16, 0, 0); } while (0)
; #define PG8_LDA(dst, b, h) do { _Pragma("unroll") for (int m = 0; m < 4; ++m) _Pragma("unroll") for (int k = 0; k < 2; ++k) dst[m][k] = *(const PG8_LAS bf16x8*)(lds + PG8_SA(b, h) + aoff + m * 2048 + k * 1024); } while (0)
; #define PG8_LDB(dst, b, h) do { _Pragma("unroll") for (int n = 0; n < 2; ++n) _Pragma("unroll") for (int k = 0; k < 2; ++k) dst[n][k] = *(const PG8_LAS bf16x8*)(lds + PG8_SB(b, h) + boff + n * 2048 + k * 1024); } while (0)
; #define PG8_MMA(ai, bj, At, Bt) do { __builtin_amdgcn_s_setprio(1); _Pragma("unroll") for (int m = 0; m < 4; ++m) _Pragma("unroll") for (int n = 0; n < 2; ++n) _Pragma("unroll") for (int k = 0; k < 2; ++k) \
;         acc[ai][bj][m][n] = __builtin_amdgcn_mfma_f32_16x16x32_bf16(Bt[n][k], At[m][k], acc[ai][bj][m][n], 0, 0, 0); __builtin_amdgcn_s_setprio(0); } while (0)
; #define PG8_WAIT_V(n) asm volatile("s_waitcnt vmcnt(" #n ")" ::: "memory")
; #define PG8_WAIT_L(n) asm volatile("s_waitcnt lgkmcnt(" #n ")" ::: "memory")
; #define PG8_BAR __builtin_amdgcn_s_barrier()
; #define PG8_SCHED __builtin_amdgcn_sched_barrier(0)
; template <class Epi, class Sched, bool ALIGN_EPI = false, bool SP2 = false>
; __device__ __forceinline__ void gemm_phase(PG8_LAS unsigned char* lds, const Gemm g, const Sched& S, const Epi& E) {
;     ...
;             PG8_WAIT_V(8); PG8_WAIT_L(0); PG8_BAR; PG8_MMA(1, 0, At, B0); PG8_MMA(1, 1, At, B1); PG8_BAR; PG8_SCHED;
;             PG8_LDB(B0, 1, 0); PG8_LDB(B1, 1, 1); PG8_SCHED; PG8_LDA(At, 1, 0); PG8_STAGE(PG8_SA(0, 1), a2 + hstep, voffA);
;             PG8_WAIT_V(8); PG8_WAIT_L(0); PG8_BAR; PG8_MMA(0, 0, At, B0); PG8_MMA(0, 1, At, B1); PG8_BAR; PG8_SCHED;
;             PG8_LDA(At, 1, 1); PG8_STAGE(PG8_SB(1, 0), b3, voffB); PG8_STAGE(PG8_SB(1, 1), b3 + hstep, voffB); PG8_STAGE(PG8_SA(1, 0), a3, voffA);
	v_mfma_f32_16x16x32_bf16 v[60:63], v[142:145], v[196:199], v[60:63]
	v_mfma_f32_16x16x32_bf16 v[56:59], v[156:159], v[196:199], v[56:59]
	v_mfma_f32_16x16x32_bf16 v[52:55], v[142:145], v[204:207], v[52:55]
	v_mfma_f32_16x16x32_bf16 v[44:47], v[156:159], v[204:207], v[44:47]
	v_mfma_f32_16x16x32_bf16 v[36:39], v[142:145], v[212:215], v[36:39]
	v_mfma_f32_16x16x32_bf16 v[28:31], v[156:159], v[212:215], v[28:31]
	v_mfma_f32_16x16x32_bf16 v[20:23], v[142:145], v[220:223], v[20:23]
	v_mfma_f32_16x16x32_bf16 v[12:15], v[156:159], v[220:223], v[12:15]
	v_mfma_f32_16x16x32_bf16 v[60:63], v[146:149], v[200:203], v[60:63]
	v_mfma_f32_16x16x32_bf16 v[56:59], v[160:163], v[200:203], v[56:59]
	v_mfma_f32_16x16x32_bf16 v[52:55], v[146:149], v[208:211], v[52:55]
	v_mfma_f32_16x16x32_bf16 v[44:47], v[160:163], v[208:211], v[44:47]
	v_mfma_f32_16x16x32_bf16 v[36:39], v[146:149], v[216:219], v[36:39]
	v_mfma_f32_16x16x32_bf16 v[28:31], v[160:163], v[216:219], v[28:31]
	v_mfma_f32_16x16x32_bf16 v[20:23], v[146:149], v[224:227], v[20:23]
	v_mfma_f32_16x16x32_bf16 v[12:15], v[160:163], v[224:227], v[12:15]
	v_mfma_f32_16x16x32_bf16 v[48:51], v[164:167], v[196:199], v[48:51]
	v_mfma_f32_16x16x32_bf16 v[40:43], v[172:175], v[196:199], v[40:43]
	v_mfma_f32_16x16x32_bf16 v[32:35], v[164:167], v[204:207], v[32:35]
	v_mfma_f32_16x16x32_bf16 v[24:27], v[172:175], v[204:207], v[24:27]
	v_mfma_f32_16x16x32_bf16 v[16:19], v[164:167], v[212:215], v[16:19]
	v_mfma_f32_16x16x32_bf16 v[8:11], v[172:175], v[212:215], v[8:11]
	v_mfma_f32_16x16x32_bf16 v[4:7], v[164:167], v[220:223], v[4:7]
	v_mfma_f32_16x16x32_bf16 v[0:3], v[172:175], v[220:223], v[0:3]
	v_mfma_f32_16x16x32_bf16 v[48:51], v[168:171], v[200:203], v[48:51]
	v_mfma_f32_16x16x32_bf16 v[40:43], v[192:195], v[200:203], v[40:43]
	v_mfma_f32_16x16x32_bf16 v[32:35], v[168:171], v[208:211], v[32:35]
	v_mfma_f32_16x16x32_bf16 v[24:27], v[192:195], v[208:211], v[24:27]
	v_mfma_f32_16x16x32_bf16 v[16:19], v[168:171], v[216:219], v[16:19]
	v_mfma_f32_16x16x32_bf16 v[8:11], v[192:195], v[216:219], v[8:11]
	v_mfma_f32_16x16x32_bf16 v[4:7], v[168:171], v[224:227], v[4:7]
	v_mfma_f32_16x16x32_bf16 v[0:3], v[192:195], v[224:227], v[0:3]
	s_barrier
	v_add_u32_e32 v155, s93, v139
	s_add_i32 s68, 0, 0x1c000
	ds_read_b128 v[142:145], v155
	ds_read_b128 v[146:149], v155 offset:1024
	ds_read_b128 v[156:159], v155 offset:2048
	ds_read_b128 v[160:163], v155 offset:3072
	v_add_u32_e32 v155, s68, v139
	ds_read_b128 v[164:167], v155
	ds_read_b128 v[168:171], v155 offset:1024
	ds_read_b128 v[172:175], v155 offset:2048
	ds_read_b128 v[192:195], v155 offset:3072
	s_add_u32 s76, s76, 0x80000
	s_addc_u32 s77, s77, 0
	s_mov_b32 m0, s22
	v_lshl_add_u64 v[190:191], s[76:77], 0, v[128:129]
	ds_read_b128 v[196:199], v141 offset:32768
	ds_read_b128 v[200:203], v141 offset:33792
	ds_read_b128 v[204:207], v141 offset:34816
	ds_read_b128 v[208:211], v141 offset:35840
	ds_read_b128 v[212:215], v141 offset:36864
	ds_read_b128 v[216:219], v141 offset:37888
	ds_read_b128 v[220:223], v141 offset:38912
	ds_read_b128 v[224:227], v141 offset:39936
	global_load_lds_dwordx4 v[190:191], off
	v_lshl_add_u64 v[190:191], s[76:77], 0, v[130:131]
	s_mov_b32 m0, s23
	s_nop 0
	global_load_lds_dwordx4 v[190:191], off
	s_waitcnt vmcnt(8)
	s_waitcnt lgkmcnt(0)
	s_barrier
	v_mfma_f32_16x16x32_bf16 v[124:127], v[142:145], v[196:199], v[124:127]
	v_mfma_f32_16x16x32_bf16 v[120:123], v[156:159], v[196:199], v[120:123]
	v_mfma_f32_16x16x32_bf16 v[116:119], v[142:145], v[204:207], v[116:119]
	v_mfma_f32_16x16x32_bf16 v[108:111], v[156:159], v[204:207], v[108:111]
	v_mfma_f32_16x16x32_bf16 v[100:103], v[142:145], v[212:215], v[100:103]
	v_mfma_f32_16x16x32_bf16 v[92:95], v[156:159], v[212:215], v[92:95]
	v_mfma_f32_16x16x32_bf16 v[84:87], v[142:145], v[220:223], v[84:87]
	v_mfma_f32_16x16x32_bf16 v[76:79], v[156:159], v[220:223], v[76:79]
	v_mfma_f32_16x16x32_bf16 v[124:127], v[146:149], v[200:203], v[124:127]
	v_mfma_f32_16x16x32_bf16 v[120:123], v[160:163], v[200:203], v[120:123]
	v_mfma_f32_16x16x32_bf16 v[116:119], v[146:149], v[208:211], v[116:119]
	v_mfma_f32_16x16x32_bf16 v[108:111], v[160:163], v[208:211], v[108:111]
	v_mfma_f32_16x16x32_bf16 v[100:103], v[146:149], v[216:219], v[100:103]
	v_mfma_f32_16x16x32_bf16 v[92:95], v[160:163], v[216:219], v[92:95]
	v_mfma_f32_16x16x32_bf16 v[84:87], v[146:149], v[224:227], v[84:87]
	v_mfma_f32_16x16x32_bf16 v[76:79], v[160:163], v[224:227], v[76:79]
	v_mfma_f32_16x16x32_bf16 v[112:115], v[164:167], v[196:199], v[112:115]
	v_mfma_f32_16x16x32_bf16 v[104:107], v[172:175], v[196:199], v[104:107]
	v_mfma_f32_16x16x32_bf16 v[96:99], v[164:167], v[204:207], v[96:99]
	v_mfma_f32_16x16x32_bf16 v[88:91], v[172:175], v[204:207], v[88:91]
	v_mfma_f32_16x16x32_bf16 v[80:83], v[164:167], v[212:215], v[80:83]
	v_mfma_f32_16x16x32_bf16 v[72:75], v[172:175], v[212:215], v[72:75]
	v_mfma_f32_16x16x32_bf16 v[68:71], v[164:167], v[220:223], v[68:71]
	v_mfma_f32_16x16x32_bf16 v[64:67], v[172:175], v[220:223], v[64:67]
	v_mfma_f32_16x16x32_bf16 v[112:115], v[168:171], v[200:203], v[112:115]
	v_mfma_f32_16x16x32_bf16 v[104:107], v[192:195], v[200:203], v[104:107]
	v_mfma_f32_16x16x32_bf16 v[96:99], v[168:171], v[208:211], v[96:99]
	v_mfma_f32_16x16x32_bf16 v[88:91], v[192:195], v[208:211], v[88:91]
	v_mfma_f32_16x16x32_bf16 v[80:83], v[168:171], v[216:219], v[80:83]
	v_mfma_f32_16x16x32_bf16 v[72:75], v[192:195], v[216:219], v[72:75]
	v_mfma_f32_16x16x32_bf16 v[68:71], v[168:171], v[224:227], v[68:71]
	v_mfma_f32_16x16x32_bf16 v[64:67], v[192:195], v[224:227], v[64:67]
	s_barrier
; #define PG8_STAGE(bufoff, gbase, voff) do { _Pragma("unroll") for (int _i = 0; _i < 2; ++_i) \
;         __builtin_amdgcn_global_load_lds((const unsigned*)((const char*)(gbase) + (voff)[_i]), (PG8_LAS unsigned*)(lds + (bufoff) + ldsw + _i * 8192), 16, 0, 0); } while (0)
; #define PG8_LDA(dst, b, h) do { _Pragma("unroll") for (int m = 0; m < 4; ++m) _Pragma("unroll") for (int k = 0; k < 2; ++k) dst[m][k] = *(const PG8_LAS bf16x8*)(lds + PG8_SA(b, h) + aoff + m * 2048 + k * 1024); } while (0)
; #define PG8_MMA(ai, bj, At, Bt) do { __builtin_amdgcn_s_setprio(1); _Pragma("unroll") for (int m = 0; m < 4; ++m) _Pragma("unroll") for (int n = 0; n < 2; ++n) _Pragma("unroll") for (int k = 0; k < 2; ++k) \
;         acc[ai][bj][m][n] = __builtin_amdgcn_mfma_f32_16x16x32_bf16(Bt[n][k], At[m][k], acc[ai][bj][m][n], 0, 0, 0); __builtin_amdgcn_s_setprio(0); } while (0)
; #define PG8_WAIT_V(n) asm volatile("s_waitcnt vmcnt(" #n ")" ::: "memory")
; #define PG8_WAIT_L(n) asm volatile("s_waitcnt lgkmcnt(" #n ")" ::: "memory")
; #define PG8_BAR __builtin_amdgcn_s_barrier()
; #define PG8_SCHED __builtin_amdgcn_sched_barrier(0)
; template <class Epi, class Sched, bool ALIGN_EPI = false, bool SP2 = false>
; __device__ __forceinline__ void gemm_phase(PG8_LAS unsigned char* lds, const Gemm g, const Sched& S, const Epi& E) {
;     ...
;         for (int t = 0; t < nt; t += 2) {
;     ...
;             PG8_LDA(At, 1, 1); PG8_STAGE(PG8_SB(1, 0), b3, voffB); PG8_STAGE(PG8_SB(1, 1), b3 + hstep, voffB); PG8_STAGE(PG8_SA(1, 0), a3, voffA);
;             PG8_WAIT_V(8); PG8_WAIT_L(0); PG8_BAR; PG8_MMA(1, 0, At, B0); PG8_MMA(1, 1, At, B1); PG8_BAR; PG8_SCHED;
	s_add_i32 s69, s93, s0
	v_lshl_add_u64 v[150:151], v[150:151], 0, s[18:19]
	s_mov_b32 m0, s69
	ds_read_b128 v[196:199], v141 offset:49152
	ds_read_b128 v[200:203], v141 offset:50176
	ds_read_b128 v[204:207], v141 offset:51200
	ds_read_b128 v[208:211], v141 offset:52224
	ds_read_b128 v[212:215], v141 offset:53248
	ds_read_b128 v[216:219], v141 offset:54272
	ds_read_b128 v[220:223], v141 offset:55296
	ds_read_b128 v[224:227], v141 offset:56320
	global_load_lds_dwordx4 v[150:151], off
	s_add_i32 m0, s69, 0x2000
	s_add_u32 s74, s74, 0x80080
	v_lshl_add_u64 v[150:151], v[182:183], 0, s[18:19]
	s_addc_u32 s75, s75, 0
	s_add_i32 s68, s68, s0
	global_load_lds_dwordx4 v[150:151], off
	v_lshl_add_u64 v[150:151], s[74:75], 0, v[152:153]
	s_mov_b32 m0, s68
	s_nop 0
	global_load_lds_dwordx4 v[150:151], off
	v_lshl_add_u64 v[150:151], s[74:75], 0, v[132:133]
	s_add_i32 m0, s68, 0x2000
	s_nop 0
	global_load_lds_dwordx4 v[150:151], off
	v_lshl_add_u64 v[150:151], v[184:185], 0, s[18:19]
	s_mov_b32 m0, s26
	s_nop 0
	global_load_lds_dwordx4 v[150:151], off
	v_lshl_add_u64 v[150:151], v[188:189], 0, s[18:19]
	s_mov_b32 m0, s34
	s_nop 0
	global_load_lds_dwordx4 v[150:151], off
	s_waitcnt vmcnt(8)
	s_waitcnt lgkmcnt(0)
	s_barrier
	v_mfma_f32_16x16x32_bf16 v[60:63], v[142:145], v[196:199], v[60:63]
	v_mfma_f32_16x16x32_bf16 v[56:59], v[156:159], v[196:199], v[56:59]
	v_mfma_f32_16x16x32_bf16 v[52:55], v[142:145], v[204:207], v[52:55]
	v_mfma_f32_16x16x32_bf16 v[44:47], v[156:159], v[204:207], v[44:47]
	v_mfma_f32_16x16x32_bf16 v[36:39], v[142:145], v[212:215], v[36:39]
	v_mfma_f32_16x16x32_bf16 v[28:31], v[156:159], v[212:215], v[28:31]
	v_mfma_f32_16x16x32_bf16 v[20:23], v[142:145], v[220:223], v[20:23]
	v_mfma_f32_16x16x32_bf16 v[12:15], v[156:159], v[220:223], v[12:15]
	v_mfma_f32_16x16x32_bf16 v[60:63], v[146:149], v[200:203], v[60:63]
	v_mfma_f32_16x16x32_bf16 v[56:59], v[160:163], v[200:203], v[56:59]
	v_mfma_f32_16x16x32_bf16 v[52:55], v[146:149], v[208:211], v[52:55]
	v_mfma_f32_16x16x32_bf16 v[44:47], v[160:163], v[208:211], v[44:47]
	v_mfma_f32_16x16x32_bf16 v[36:39], v[146:149], v[216:219], v[36:39]
	v_mfma_f32_16x16x32_bf16 v[28:31], v[160:163], v[216:219], v[28:31]
	v_mfma_f32_16x16x32_bf16 v[20:23], v[146:149], v[224:227], v[20:23]
	v_mfma_f32_16x16x32_bf16 v[12:15], v[160:163], v[224:227], v[12:15]
	v_mfma_f32_16x16x32_bf16 v[48:51], v[164:167], v[196:199], v[48:51]
	v_mfma_f32_16x16x32_bf16 v[40:43], v[172:175], v[196:199], v[40:43]
	v_mfma_f32_16x16x32_bf16 v[32:35], v[164:167], v[204:207], v[32:35]
	v_mfma_f32_16x16x32_bf16 v[24:27], v[172:175], v[204:207], v[24:27]
	v_mfma_f32_16x16x32_bf16 v[16:19], v[164:167], v[212:215], v[16:19]
	v_mfma_f32_16x16x32_bf16 v[8:11], v[172:175], v[212:215], v[8:11]
	v_mfma_f32_16x16x32_bf16 v[4:7], v[164:167], v[220:223], v[4:7]
	v_mfma_f32_16x16x32_bf16 v[0:3], v[172:175], v[220:223], v[0:3]
	v_mfma_f32_16x16x32_bf16 v[48:51], v[168:171], v[200:203], v[48:51]
	v_mfma_f32_16x16x32_bf16 v[40:43], v[192:195], v[200:203], v[40:43]
	v_mfma_f32_16x16x32_bf16 v[32:35], v[168:171], v[208:211], v[32:35]
	v_mfma_f32_16x16x32_bf16 v[24:27], v[192:195], v[208:211], v[24:27]
	v_mfma_f32_16x16x32_bf16 v[16:19], v[168:171], v[216:219], v[16:19]
	v_mfma_f32_16x16x32_bf16 v[8:11], v[192:195], v[216:219], v[8:11]
	v_mfma_f32_16x16x32_bf16 v[4:7], v[168:171], v[224:227], v[4:7]
	v_mfma_f32_16x16x32_bf16 v[0:3], v[192:195], v[224:227], v[0:3]
	s_barrier
	s_add_i32 s71, s71, 2
	s_add_u32 s48, s48, 0x100
	s_addc_u32 s49, s49, 0
	s_add_u32 s59, s59, 0x100
	s_addc_u32 s63, s63, 0
	s_cmp_gt_u32 s71, 29
	s_cbranch_scc0 .LBB0_354
	s_and_b64 vcc, exec, s[28:29]
	s_movk_i32 s58, 0x5fe
	s_movk_i32 s59, 0x1810
	s_cbranch_vccz .LBB0_357
	s_barrier

; __global__ void __launch_bounds__(512, 2) fwd_mega(Args args) {
	.amdhsa_kernel _Z8fwd_mega4Args
		.amdhsa_group_segment_fixed_size 0
		.amdhsa_private_segment_fixed_size 0
		.amdhsa_kernarg_size 488
		.amdhsa_user_sgpr_count 2
		.amdhsa_user_sgpr_dispatch_ptr 0
		.amdhsa_user_sgpr_queue_ptr 0
		.amdhsa_user_sgpr_kernarg_segment_ptr 1
		.amdhsa_user_sgpr_dispatch_id 0
		.amdhsa_user_sgpr_kernarg_preload_length 0
		.amdhsa_user_sgpr_kernarg_preload_offset 0
		.amdhsa_user_sgpr_private_segment_size 0
		.amdhsa_uses_dynamic_stack 0
		.amdhsa_enable_private_segment 0
		.amdhsa_system_sgpr_workgroup_id_x 1
		.amdhsa_system_sgpr_workgroup_id_y 0
		.amdhsa_system_sgpr_workgroup_id_z 0
		.amdhsa_system_sgpr_workgroup_info 0
		.amdhsa_system_vgpr_workitem_id 2
		.amdhsa_next_free_vgpr 256
		.amdhsa_next_free_sgpr 100
		.amdhsa_accum_offset 256
		.amdhsa_reserve_vcc 1
		.amdhsa_float_round_mode_32 0
		.amdhsa_float_round_mode_16_64 0
		.amdhsa_float_denorm_mode_32 3
		.amdhsa_float_denorm_mode_16_64 3
		.amdhsa_dx10_clamp 1
		.amdhsa_ieee_mode 1
		.amdhsa_fp16_overflow 0
		.amdhsa_tg_split 0
		.amdhsa_exception_fp_ieee_invalid_op 0
		.amdhsa_exception_fp_denorm_src 0
		.amdhsa_exception_fp_ieee_div_zero 0
		.amdhsa_exception_fp_ieee_overflow 0
		.amdhsa_exception_fp_ieee_underflow 0
		.amdhsa_exception_fp_ieee_inexact 0
		.amdhsa_exception_int_div_zero 0
	.end_amdhsa_kernel

; __global__ void __launch_bounds__(512, 2) fwd_mega(Args args) {
amdhsa.kernels:
  - .agpr_count:     0
    .args:
      - .offset:         0
        .size:           232
        .value_kind:     by_value
      - .offset:         232
        .size:           4
        .value_kind:     hidden_block_count_x
      - .offset:         236
        .size:           4
        .value_kind:     hidden_block_count_y
      - .offset:         240
        .size:           4
        .value_kind:     hidden_block_count_z
      - .offset:         244
        .size:           2
        .value_kind:     hidden_group_size_x
      - .offset:         246
        .size:           2
        .value_kind:     hidden_group_size_y
      - .offset:         248
        .size:           2
        .value_kind:     hidden_group_size_z
      - .offset:         250
        .size:           2
        .value_kind:     hidden_remainder_x
      - .offset:         252
        .size:           2
        .value_kind:     hidden_remainder_y
      - .offset:         254
        .size:           2
        .value_kind:     hidden_remainder_z
      - .offset:         272
        .size:           8
        .value_kind:     hidden_global_offset_x
      - .offset:         280
        .size:           8
        .value_kind:     hidden_global_offset_y
      - .offset:         288
        .size:           8
        .value_kind:     hidden_global_offset_z
      - .offset:         296
        .size:           2
        .value_kind:     hidden_grid_dims
      - .offset:         320
        .size:           8
        .value_kind:     hidden_multigrid_sync_arg
      - .offset:         352
        .size:           4
        .value_kind:     hidden_dynamic_lds_size
    .group_segment_fixed_size: 0
    .kernarg_segment_align: 8
    .kernarg_segment_size: 488
    .language:       OpenCL C
    .language_version:
      - 2
      - 0
    .max_flat_workgroup_size: 512
    .name:           _Z8fwd_mega4Args
    .private_segment_fixed_size: 0
    .sgpr_count:     106
    .sgpr_spill_count: 196
    .symbol:         _Z8fwd_mega4Args.kd
    .uniform_work_group_size: 1
    .uses_dynamic_stack: false
    .vgpr_count:     256
    .vgpr_spill_count: 0
    .wavefront_size: 64
